# removes the duplicated lgkmcnt(0) wait ahead of each GEMM MFMA segment (36 sites) on top of the previous version
# speedup vs baseline: 1.0295x; 1.0014x over previous
.LBB0_95:
	s_add_u32 s16, s14, 0xfff80080
	s_addc_u32 s17, s15, -1
	s_add_i32 s42, 0, 0x10000
	v_add_u32_e32 v145, s42, v142
	ds_read_b128 v[146:149], v145
	ds_read_b128 v[150:153], v145 offset:1024
	ds_read_b128 v[154:157], v145 offset:2048
	ds_read_b128 v[158:161], v145 offset:3072
	s_cmp_eq_u32 s41, 28
	s_cselect_b32 s19, s9, s17
	s_cselect_b32 s18, s37, s16
	s_cselect_b32 s17, s7, s40
	s_cselect_b32 s16, s38, s39
	s_add_i32 m0, s27, 0xc000
	ds_read_b128 v[162:165], v144
	ds_read_b128 v[166:169], v144 offset:1024
	ds_read_b128 v[170:173], v144 offset:2048
	ds_read_b128 v[174:177], v144 offset:3072
	ds_read_b128 v[178:181], v144 offset:4096
	ds_read_b128 v[182:185], v144 offset:5120
	ds_read_b128 v[186:189], v144 offset:6144
	ds_read_b128 v[190:193], v144 offset:7168
	global_load_lds_dwordx4 v138, s[14:15]
	s_add_i32 m0, s27, 0xe000
	s_nop 0
	global_load_lds_dwordx4 v140, s[14:15]
	s_waitcnt lgkmcnt(8)
	s_barrier
	s_waitcnt lgkmcnt(0)
	s_setprio 1
	v_mfma_f32_16x16x32_bf16 v[128:131], v[146:149], v[162:165], v[128:131]
	v_mfma_f32_16x16x32_bf16 v[128:131], v[150:153], v[166:169], v[128:131]
	v_mfma_f32_16x16x32_bf16 v[120:123], v[150:153], v[174:177], v[120:123]
	v_mfma_f32_16x16x32_bf16 v[120:123], v[146:149], v[170:173], v[120:123]
	v_mfma_f32_16x16x32_bf16 v[104:107], v[146:149], v[178:181], v[104:107]
	v_mfma_f32_16x16x32_bf16 v[104:107], v[150:153], v[182:185], v[104:107]
	v_mfma_f32_16x16x32_bf16 v[88:91], v[150:153], v[190:193], v[88:91]
	v_mfma_f32_16x16x32_bf16 v[88:91], v[146:149], v[186:189], v[88:91]
	v_mfma_f32_16x16x32_bf16 v[84:87], v[154:157], v[186:189], v[84:87]
	v_mfma_f32_16x16x32_bf16 v[84:87], v[158:161], v[190:193], v[84:87]
	v_mfma_f32_16x16x32_bf16 v[100:103], v[158:161], v[182:185], v[100:103]
	v_mfma_f32_16x16x32_bf16 v[100:103], v[154:157], v[178:181], v[100:103]
	v_mfma_f32_16x16x32_bf16 v[116:119], v[154:157], v[170:173], v[116:119]
	v_mfma_f32_16x16x32_bf16 v[116:119], v[158:161], v[174:177], v[116:119]
	v_mfma_f32_16x16x32_bf16 v[124:127], v[158:161], v[166:169], v[124:127]
	s_barrier
	v_mfma_f32_16x16x32_bf16 v[124:127], v[154:157], v[162:165], v[124:127]
	s_setprio 0
	s_add_i32 s44, 0, 0x14000
	s_add_i32 s42, s42, s26
	v_add_u32_e32 v145, s44, v142
	v_lshl_add_u64 v[212:213], s[16:17], 0, v[2:3]
	s_mov_b32 m0, s42
	ds_read_b128 v[194:197], v145
	ds_read_b128 v[200:203], v145 offset:1024
	ds_read_b128 v[204:207], v145 offset:2048
	ds_read_b128 v[208:211], v145 offset:3072
	global_load_lds_dwordx4 v[212:213], off
	v_lshl_add_u64 v[214:215], s[16:17], 0, v[132:133]
	s_add_i32 m0, s42, 0x2000
	s_nop 0
	global_load_lds_dwordx4 v[214:215], off
	s_barrier
	s_waitcnt lgkmcnt(0)
	s_setprio 1
	v_mfma_f32_16x16x32_bf16 v[112:115], v[194:197], v[162:165], v[112:115]
	v_mfma_f32_16x16x32_bf16 v[112:115], v[200:203], v[166:169], v[112:115]
	v_mfma_f32_16x16x32_bf16 v[96:99], v[200:203], v[174:177], v[96:99]
	v_mfma_f32_16x16x32_bf16 v[96:99], v[194:197], v[170:173], v[96:99]
	v_mfma_f32_16x16x32_bf16 v[80:83], v[194:197], v[178:181], v[80:83]
	v_mfma_f32_16x16x32_bf16 v[80:83], v[200:203], v[182:185], v[80:83]
	v_mfma_f32_16x16x32_bf16 v[72:75], v[200:203], v[190:193], v[72:75]
	v_mfma_f32_16x16x32_bf16 v[72:75], v[194:197], v[186:189], v[72:75]
	v_mfma_f32_16x16x32_bf16 v[68:71], v[204:207], v[186:189], v[68:71]
	v_mfma_f32_16x16x32_bf16 v[68:71], v[208:211], v[190:193], v[68:71]
	v_mfma_f32_16x16x32_bf16 v[76:79], v[208:211], v[182:185], v[76:79]
	v_mfma_f32_16x16x32_bf16 v[76:79], v[204:207], v[178:181], v[76:79]
	v_mfma_f32_16x16x32_bf16 v[92:95], v[204:207], v[170:173], v[92:95]
	v_mfma_f32_16x16x32_bf16 v[92:95], v[208:211], v[174:177], v[92:95]
	v_mfma_f32_16x16x32_bf16 v[108:111], v[208:211], v[166:169], v[108:111]
	s_barrier
	v_mfma_f32_16x16x32_bf16 v[108:111], v[204:207], v[162:165], v[108:111]
	s_setprio 0
	s_mov_b32 m0, s27
	v_lshl_add_u64 v[216:217], s[18:19], 0, v[136:137]
	ds_read_b128 v[162:165], v144 offset:16384
	ds_read_b128 v[166:169], v144 offset:17408
	ds_read_b128 v[170:173], v144 offset:18432
	ds_read_b128 v[174:177], v144 offset:19456
	ds_read_b128 v[178:181], v144 offset:20480
	ds_read_b128 v[182:185], v144 offset:21504
	ds_read_b128 v[186:189], v144 offset:22528
	ds_read_b128 v[190:193], v144 offset:23552
	global_load_lds_dwordx4 v[216:217], off
	v_lshl_add_u64 v[218:219], s[18:19], 0, v[134:135]
	s_mov_b32 m0, s28
	s_nop 0
	global_load_lds_dwordx4 v[218:219], off
	s_waitcnt vmcnt(10)
	s_barrier
	s_waitcnt lgkmcnt(0)
	s_setprio 1
	v_mfma_f32_16x16x32_bf16 v[64:67], v[146:149], v[162:165], v[64:67]
	v_mfma_f32_16x16x32_bf16 v[64:67], v[150:153], v[166:169], v[64:67]
	v_mfma_f32_16x16x32_bf16 v[56:59], v[150:153], v[174:177], v[56:59]
	v_mfma_f32_16x16x32_bf16 v[56:59], v[146:149], v[170:173], v[56:59]
	v_mfma_f32_16x16x32_bf16 v[40:43], v[146:149], v[178:181], v[40:43]
	v_mfma_f32_16x16x32_bf16 v[40:43], v[150:153], v[182:185], v[40:43]
	v_mfma_f32_16x16x32_bf16 v[24:27], v[150:153], v[190:193], v[24:27]
	v_mfma_f32_16x16x32_bf16 v[24:27], v[146:149], v[186:189], v[24:27]
	v_mfma_f32_16x16x32_bf16 v[20:23], v[154:157], v[186:189], v[20:23]
	v_mfma_f32_16x16x32_bf16 v[20:23], v[158:161], v[190:193], v[20:23]
	v_mfma_f32_16x16x32_bf16 v[36:39], v[158:161], v[182:185], v[36:39]
	v_mfma_f32_16x16x32_bf16 v[36:39], v[154:157], v[178:181], v[36:39]
	v_mfma_f32_16x16x32_bf16 v[52:55], v[154:157], v[170:173], v[52:55]
	v_mfma_f32_16x16x32_bf16 v[52:55], v[158:161], v[174:177], v[52:55]
	v_mfma_f32_16x16x32_bf16 v[60:63], v[158:161], v[166:169], v[60:63]
	s_barrier
	v_mfma_f32_16x16x32_bf16 v[60:63], v[154:157], v[162:165], v[60:63]
	s_setprio 0
	s_add_u32 s42, s16, 0x20000
	s_addc_u32 s43, s17, 0
	s_add_i32 s44, s44, s26
	s_mov_b32 m0, s44
	s_nop 0
	global_load_lds_dwordx4 v2, s[42:43]
	s_add_i32 m0, s44, 0x2000
	s_nop 0
	global_load_lds_dwordx4 v132, s[42:43]
	s_add_i32 s42, 0, 0x18000
	v_add_u32_e32 v145, s42, v142
	ds_read_b128 v[146:149], v145
	ds_read_b128 v[150:153], v145 offset:1024
	ds_read_b128 v[154:157], v145 offset:2048
	ds_read_b128 v[158:161], v145 offset:3072
	s_waitcnt vmcnt(6)
	s_barrier
	s_setprio 1
	v_mfma_f32_16x16x32_bf16 v[48:51], v[194:197], v[162:165], v[48:51]
	v_mfma_f32_16x16x32_bf16 v[48:51], v[200:203], v[166:169], v[48:51]
	v_mfma_f32_16x16x32_bf16 v[32:35], v[200:203], v[174:177], v[32:35]
	v_mfma_f32_16x16x32_bf16 v[32:35], v[194:197], v[170:173], v[32:35]
	v_mfma_f32_16x16x32_bf16 v[16:19], v[194:197], v[178:181], v[16:19]
	v_mfma_f32_16x16x32_bf16 v[16:19], v[200:203], v[182:185], v[16:19]
	v_mfma_f32_16x16x32_bf16 v[8:11], v[200:203], v[190:193], v[8:11]
	v_mfma_f32_16x16x32_bf16 v[8:11], v[194:197], v[186:189], v[8:11]
	v_mfma_f32_16x16x32_bf16 v[4:7], v[204:207], v[186:189], v[4:7]
	v_mfma_f32_16x16x32_bf16 v[4:7], v[208:211], v[190:193], v[4:7]
	v_mfma_f32_16x16x32_bf16 v[12:15], v[208:211], v[182:185], v[12:15]
	v_mfma_f32_16x16x32_bf16 v[12:15], v[204:207], v[178:181], v[12:15]
	v_mfma_f32_16x16x32_bf16 v[28:31], v[204:207], v[170:173], v[28:31]
	v_mfma_f32_16x16x32_bf16 v[28:31], v[208:211], v[174:177], v[28:31]
	v_mfma_f32_16x16x32_bf16 v[44:47], v[208:211], v[166:169], v[44:47]
	s_barrier
	v_mfma_f32_16x16x32_bf16 v[44:47], v[204:207], v[162:165], v[44:47]
	s_setprio 0
	s_add_u32 s18, s18, 0x80000
	s_addc_u32 s19, s19, 0
	s_mov_b32 m0, s29
	ds_read_b128 v[162:165], v144 offset:32768
	ds_read_b128 v[166:169], v144 offset:33792
	ds_read_b128 v[170:173], v144 offset:34816
	ds_read_b128 v[174:177], v144 offset:35840
	ds_read_b128 v[178:181], v144 offset:36864
	ds_read_b128 v[182:185], v144 offset:37888
	ds_read_b128 v[186:189], v144 offset:38912
	ds_read_b128 v[190:193], v144 offset:39936
	global_load_lds_dwordx4 v136, s[18:19]
	s_mov_b32 m0, s30
	s_nop 0
	global_load_lds_dwordx4 v134, s[18:19]
	s_waitcnt lgkmcnt(8)
	s_barrier
	s_waitcnt lgkmcnt(0)
	s_setprio 1
	v_mfma_f32_16x16x32_bf16 v[128:131], v[146:149], v[162:165], v[128:131]
	v_mfma_f32_16x16x32_bf16 v[128:131], v[150:153], v[166:169], v[128:131]
	v_mfma_f32_16x16x32_bf16 v[120:123], v[150:153], v[174:177], v[120:123]
	v_mfma_f32_16x16x32_bf16 v[120:123], v[146:149], v[170:173], v[120:123]
	v_mfma_f32_16x16x32_bf16 v[104:107], v[146:149], v[178:181], v[104:107]
	v_mfma_f32_16x16x32_bf16 v[104:107], v[150:153], v[182:185], v[104:107]
	v_mfma_f32_16x16x32_bf16 v[88:91], v[150:153], v[190:193], v[88:91]
	v_mfma_f32_16x16x32_bf16 v[88:91], v[146:149], v[186:189], v[88:91]
	v_mfma_f32_16x16x32_bf16 v[84:87], v[154:157], v[186:189], v[84:87]
	v_mfma_f32_16x16x32_bf16 v[84:87], v[158:161], v[190:193], v[84:87]
	v_mfma_f32_16x16x32_bf16 v[100:103], v[158:161], v[182:185], v[100:103]
	v_mfma_f32_16x16x32_bf16 v[100:103], v[154:157], v[178:181], v[100:103]
	v_mfma_f32_16x16x32_bf16 v[116:119], v[154:157], v[170:173], v[116:119]
	v_mfma_f32_16x16x32_bf16 v[116:119], v[158:161], v[174:177], v[116:119]
	v_mfma_f32_16x16x32_bf16 v[124:127], v[158:161], v[166:169], v[124:127]
	s_barrier
	v_mfma_f32_16x16x32_bf16 v[124:127], v[154:157], v[162:165], v[124:127]
	s_setprio 0
	s_add_i32 s18, 0, 0x1c000
	s_add_i32 s19, s42, s26
	v_add_u32_e32 v145, s18, v142
	v_lshl_add_u64 v[212:213], v[212:213], 0, s[2:3]
	s_mov_b32 m0, s19
	ds_read_b128 v[194:197], v145
	ds_read_b128 v[200:203], v145 offset:1024
	ds_read_b128 v[204:207], v145 offset:2048
	ds_read_b128 v[208:211], v145 offset:3072
	global_load_lds_dwordx4 v[212:213], off
	v_lshl_add_u64 v[212:213], v[214:215], 0, s[2:3]
	s_add_i32 m0, s19, 0x2000
	s_nop 0
	global_load_lds_dwordx4 v[212:213], off
	s_barrier
	s_waitcnt lgkmcnt(0)
	s_setprio 1
	v_mfma_f32_16x16x32_bf16 v[112:115], v[194:197], v[162:165], v[112:115]
	v_mfma_f32_16x16x32_bf16 v[112:115], v[200:203], v[166:169], v[112:115]
	v_mfma_f32_16x16x32_bf16 v[96:99], v[200:203], v[174:177], v[96:99]
	v_mfma_f32_16x16x32_bf16 v[96:99], v[194:197], v[170:173], v[96:99]
	v_mfma_f32_16x16x32_bf16 v[80:83], v[194:197], v[178:181], v[80:83]
	v_mfma_f32_16x16x32_bf16 v[80:83], v[200:203], v[182:185], v[80:83]
	v_mfma_f32_16x16x32_bf16 v[72:75], v[200:203], v[190:193], v[72:75]
	v_mfma_f32_16x16x32_bf16 v[72:75], v[194:197], v[186:189], v[72:75]
	v_mfma_f32_16x16x32_bf16 v[68:71], v[204:207], v[186:189], v[68:71]
	v_mfma_f32_16x16x32_bf16 v[68:71], v[208:211], v[190:193], v[68:71]
	v_mfma_f32_16x16x32_bf16 v[76:79], v[208:211], v[182:185], v[76:79]
	v_mfma_f32_16x16x32_bf16 v[76:79], v[204:207], v[178:181], v[76:79]
	v_mfma_f32_16x16x32_bf16 v[92:95], v[204:207], v[170:173], v[92:95]
	v_mfma_f32_16x16x32_bf16 v[92:95], v[208:211], v[174:177], v[92:95]
	v_mfma_f32_16x16x32_bf16 v[108:111], v[208:211], v[166:169], v[108:111]
	s_barrier
	v_mfma_f32_16x16x32_bf16 v[108:111], v[204:207], v[162:165], v[108:111]
	s_setprio 0
	s_mov_b32 m0, s31
	v_lshl_add_u64 v[212:213], v[216:217], 0, s[2:3]
	ds_read_b128 v[162:165], v144 offset:49152
	ds_read_b128 v[166:169], v144 offset:50176
	ds_read_b128 v[170:173], v144 offset:51200
	ds_read_b128 v[174:177], v144 offset:52224
	ds_read_b128 v[178:181], v144 offset:53248
	ds_read_b128 v[182:185], v144 offset:54272
	ds_read_b128 v[186:189], v144 offset:55296
	ds_read_b128 v[190:193], v144 offset:56320
	global_load_lds_dwordx4 v[212:213], off
	v_lshl_add_u64 v[212:213], v[218:219], 0, s[2:3]
	s_mov_b32 m0, s33
	s_nop 0
	global_load_lds_dwordx4 v[212:213], off
	s_barrier
	s_waitcnt lgkmcnt(0)
	s_setprio 1
	v_mfma_f32_16x16x32_bf16 v[64:67], v[146:149], v[162:165], v[64:67]
	v_mfma_f32_16x16x32_bf16 v[64:67], v[150:153], v[166:169], v[64:67]
	v_mfma_f32_16x16x32_bf16 v[56:59], v[150:153], v[174:177], v[56:59]
	v_mfma_f32_16x16x32_bf16 v[56:59], v[146:149], v[170:173], v[56:59]
	v_mfma_f32_16x16x32_bf16 v[40:43], v[146:149], v[178:181], v[40:43]
	v_mfma_f32_16x16x32_bf16 v[40:43], v[150:153], v[182:185], v[40:43]
	v_mfma_f32_16x16x32_bf16 v[24:27], v[150:153], v[190:193], v[24:27]
	v_mfma_f32_16x16x32_bf16 v[24:27], v[146:149], v[186:189], v[24:27]
	v_mfma_f32_16x16x32_bf16 v[20:23], v[154:157], v[186:189], v[20:23]
	v_mfma_f32_16x16x32_bf16 v[20:23], v[158:161], v[190:193], v[20:23]
	v_mfma_f32_16x16x32_bf16 v[36:39], v[158:161], v[182:185], v[36:39]
	v_mfma_f32_16x16x32_bf16 v[36:39], v[154:157], v[178:181], v[36:39]
	v_mfma_f32_16x16x32_bf16 v[52:55], v[154:157], v[170:173], v[52:55]
	v_mfma_f32_16x16x32_bf16 v[52:55], v[158:161], v[174:177], v[52:55]
	v_mfma_f32_16x16x32_bf16 v[60:63], v[158:161], v[166:169], v[60:63]
	s_barrier
	v_mfma_f32_16x16x32_bf16 v[60:63], v[154:157], v[162:165], v[60:63]
	s_setprio 0
	s_add_u32 s16, s16, 0x20080
	s_addc_u32 s17, s17, 0
	s_add_i32 s18, s18, s26
	s_mov_b32 m0, s18
	s_nop 0
	global_load_lds_dwordx4 v2, s[16:17]
	s_add_i32 m0, s18, 0x2000
	s_nop 0
	global_load_lds_dwordx4 v132, s[16:17]
	s_waitcnt vmcnt(6)
	s_barrier
	s_setprio 1
	v_mfma_f32_16x16x32_bf16 v[48:51], v[194:197], v[162:165], v[48:51]
	v_mfma_f32_16x16x32_bf16 v[48:51], v[200:203], v[166:169], v[48:51]
	v_mfma_f32_16x16x32_bf16 v[32:35], v[200:203], v[174:177], v[32:35]
	v_mfma_f32_16x16x32_bf16 v[32:35], v[194:197], v[170:173], v[32:35]
	v_mfma_f32_16x16x32_bf16 v[16:19], v[194:197], v[178:181], v[16:19]
	v_mfma_f32_16x16x32_bf16 v[16:19], v[200:203], v[182:185], v[16:19]
	v_mfma_f32_16x16x32_bf16 v[8:11], v[200:203], v[190:193], v[8:11]
	v_mfma_f32_16x16x32_bf16 v[8:11], v[194:197], v[186:189], v[8:11]
	v_mfma_f32_16x16x32_bf16 v[4:7], v[204:207], v[186:189], v[4:7]
	v_mfma_f32_16x16x32_bf16 v[4:7], v[208:211], v[190:193], v[4:7]
	v_mfma_f32_16x16x32_bf16 v[12:15], v[208:211], v[182:185], v[12:15]
	v_mfma_f32_16x16x32_bf16 v[12:15], v[204:207], v[178:181], v[12:15]
	v_mfma_f32_16x16x32_bf16 v[28:31], v[204:207], v[170:173], v[28:31]
	v_mfma_f32_16x16x32_bf16 v[28:31], v[208:211], v[174:177], v[28:31]
	v_mfma_f32_16x16x32_bf16 v[44:47], v[208:211], v[166:169], v[44:47]
	s_barrier
	v_mfma_f32_16x16x32_bf16 v[44:47], v[204:207], v[162:165], v[44:47]
	s_setprio 0
	s_add_i32 s41, s41, 2
	s_add_u32 s14, s14, 0x100
	s_addc_u32 s15, s15, 0
	s_add_u32 s39, s39, 0x100
	s_addc_u32 s40, s40, 0
	s_cmp_gt_u32 s41, 29
	s_cbranch_scc0 .LBB0_95
	v_lshl_add_u32 v145, s36, 8, v1
	v_lshl_or_b32 v146, s35, 8, v143
	v_ashrrev_i32_e32 v147, 31, v146
	v_mov_b64_e32 v[148:149], s[4:5]
	s_mov_b32 s7, 0x8200
	v_cvt_pk_bf16_f32 v72, v72, v73
	v_cvt_pk_bf16_f32 v73, v74, v75
	v_cvt_pk_bf16_f32 v74, v68, v69
	v_add_u32_e32 v68, 0x80, v145
	v_mad_i64_i32 v[150:151], s[14:15], v145, s7, v[148:149]
	v_lshlrev_b64 v[146:147], 1, v[146:147]
	v_cvt_pk_bf16_f32 v112, v112, v113
	v_cvt_pk_bf16_f32 v113, v114, v115
	v_cvt_pk_bf16_f32 v114, v108, v109
	v_or_b32_e32 v108, 16, v145
	v_mad_i64_i32 v[68:69], s[14:15], v68, s7, v[148:149]
	v_cvt_pk_bf16_f32 v48, v48, v49
	v_cvt_pk_bf16_f32 v49, v50, v51
	v_cvt_pk_bf16_f32 v50, v44, v45
	v_add_u32_e32 v44, 0x90, v145
	v_lshl_add_u64 v[150:151], v[150:151], 0, v[146:147]
	v_cvt_pk_bf16_f32 v115, v110, v111
	v_mad_i64_i32 v[108:109], s[14:15], v108, s7, v[148:149]
	v_cvt_pk_bf16_f32 v96, v96, v97
	v_cvt_pk_bf16_f32 v97, v98, v99
	v_cvt_pk_bf16_f32 v98, v92, v93
	v_or_b32_e32 v92, 32, v145
	v_lshl_add_u64 v[68:69], v[68:69], 0, v[146:147]
	v_cvt_pk_bf16_f32 v51, v46, v47
	v_mad_i64_i32 v[44:45], s[14:15], v44, s7, v[148:149]
	v_cvt_pk_bf16_f32 v32, v32, v33
	v_cvt_pk_bf16_f32 v33, v34, v35
	v_cvt_pk_bf16_f32 v34, v28, v29
	v_add_u32_e32 v28, 0xa0, v145
	global_store_dwordx4 v[150:151], v[112:115], off offset:64 nt
	v_cvt_pk_bf16_f32 v99, v94, v95
	v_mad_i64_i32 v[92:93], s[14:15], v92, s7, v[148:149]
	v_lshl_add_u64 v[112:113], v[108:109], 0, v[146:147]
	v_cvt_pk_bf16_f32 v80, v80, v81
	v_cvt_pk_bf16_f32 v81, v82, v83
	v_cvt_pk_bf16_f32 v82, v76, v77
	v_or_b32_e32 v76, 48, v145
	global_store_dwordx4 v[68:69], v[48:51], off offset:64 nt
	v_cvt_pk_bf16_f32 v35, v30, v31
	v_mad_i64_i32 v[28:29], s[14:15], v28, s7, v[148:149]
	v_lshl_add_u64 v[48:49], v[44:45], 0, v[146:147]
	v_cvt_pk_bf16_f32 v16, v16, v17
	v_cvt_pk_bf16_f32 v17, v18, v19
	v_cvt_pk_bf16_f32 v18, v12, v13
	v_add_u32_e32 v12, 0xb0, v145
	global_store_dwordx4 v[112:113], v[96:99], off offset:64 nt
	v_cvt_pk_bf16_f32 v83, v78, v79
	v_mad_i64_i32 v[76:77], s[14:15], v76, s7, v[148:149]
	v_lshl_add_u64 v[96:97], v[92:93], 0, v[146:147]
	global_store_dwordx4 v[48:49], v[32:35], off offset:64 nt
	v_cvt_pk_bf16_f32 v19, v14, v15
	v_mad_i64_i32 v[12:13], s[14:15], v12, s7, v[148:149]
	v_lshl_add_u64 v[32:33], v[28:29], 0, v[146:147]
	v_cvt_pk_bf16_f32 v128, v128, v129
	v_cvt_pk_bf16_f32 v129, v130, v131
	v_cvt_pk_bf16_f32 v130, v124, v125
	v_cvt_pk_bf16_f32 v131, v126, v127
	v_cvt_pk_bf16_f32 v108, v120, v121
	v_cvt_pk_bf16_f32 v109, v122, v123
	v_cvt_pk_bf16_f32 v110, v116, v117
	v_cvt_pk_bf16_f32 v111, v118, v119
	v_cvt_pk_bf16_f32 v92, v104, v105
	v_cvt_pk_bf16_f32 v93, v106, v107
	v_cvt_pk_bf16_f32 v94, v100, v101
	v_cvt_pk_bf16_f32 v95, v102, v103
	global_store_dwordx4 v[96:97], v[80:83], off offset:64 nt
	v_cvt_pk_bf16_f32 v78, v84, v85
	v_cvt_pk_bf16_f32 v79, v86, v87
	v_lshl_add_u64 v[80:81], v[76:77], 0, v[146:147]
	v_cvt_pk_bf16_f32 v76, v88, v89
	v_cvt_pk_bf16_f32 v77, v90, v91
	v_cvt_pk_bf16_f32 v75, v70, v71
	v_cvt_pk_bf16_f32 v64, v64, v65
	v_cvt_pk_bf16_f32 v65, v66, v67
	v_cvt_pk_bf16_f32 v66, v60, v61
	v_cvt_pk_bf16_f32 v67, v62, v63
	v_cvt_pk_bf16_f32 v44, v56, v57
	v_cvt_pk_bf16_f32 v45, v58, v59
	v_cvt_pk_bf16_f32 v46, v52, v53
	v_cvt_pk_bf16_f32 v47, v54, v55
	v_cvt_pk_bf16_f32 v28, v40, v41
	v_cvt_pk_bf16_f32 v29, v42, v43
	v_cvt_pk_bf16_f32 v30, v36, v37
	v_cvt_pk_bf16_f32 v31, v38, v39
	global_store_dwordx4 v[32:33], v[16:19], off offset:64 nt
	v_cvt_pk_bf16_f32 v14, v20, v21
	v_cvt_pk_bf16_f32 v15, v22, v23
	v_lshl_add_u64 v[16:17], v[12:13], 0, v[146:147]
	v_cvt_pk_bf16_f32 v12, v24, v25
	v_cvt_pk_bf16_f32 v13, v26, v27
	v_cvt_pk_bf16_f32 v8, v8, v9
	v_cvt_pk_bf16_f32 v9, v10, v11
	v_cvt_pk_bf16_f32 v10, v4, v5
	v_cvt_pk_bf16_f32 v11, v6, v7
	s_and_b64 vcc, exec, s[0:1]
	s_mov_b32 s35, s6
	s_mov_b32 s36, s8
	s_mov_b64 s[16:17], s[12:13]
	s_mov_b64 s[14:15], s[10:11]
	global_store_dwordx4 v[150:151], v[128:131], off nt
	global_store_dwordx4 v[112:113], v[108:111], off nt
	global_store_dwordx4 v[96:97], v[92:95], off nt
	global_store_dwordx4 v[80:81], v[76:79], off nt
	global_store_dwordx4 v[80:81], v[72:75], off offset:64 nt
	global_store_dwordx4 v[68:69], v[64:67], off nt
	global_store_dwordx4 v[48:49], v[44:47], off nt
	global_store_dwordx4 v[32:33], v[28:31], off nt
	global_store_dwordx4 v[16:17], v[12:15], off nt
	global_store_dwordx4 v[16:17], v[8:11], off offset:64 nt
	s_cbranch_vccz .LBB0_92
	s_waitcnt vmcnt(0)
	s_cmpk_gt_u32 s21, 0xff
	s_cbranch_scc1 .LBB0_99
	s_barrier

.LBB0_236:
	s_add_u32 s16, s14, 0xfffe0080
	s_addc_u32 s17, s15, -1
	s_add_i32 s41, 0, 0x10000
	v_add_u32_e32 v145, s41, v142
	ds_read_b128 v[146:149], v145
	ds_read_b128 v[150:153], v145 offset:1024
	ds_read_b128 v[154:157], v145 offset:2048
	ds_read_b128 v[158:161], v145 offset:3072
	s_cmp_eq_u32 s40, 4
	s_cselect_b32 s19, s9, s17
	s_cselect_b32 s18, s36, s16
	s_cselect_b32 s17, s7, s39
	s_cselect_b32 s16, s37, s38
	s_add_i32 m0, s26, 0xc000
	ds_read_b128 v[162:165], v144
	ds_read_b128 v[166:169], v144 offset:1024
	ds_read_b128 v[170:173], v144 offset:2048
	ds_read_b128 v[174:177], v144 offset:3072
	ds_read_b128 v[178:181], v144 offset:4096
	ds_read_b128 v[182:185], v144 offset:5120
	ds_read_b128 v[186:189], v144 offset:6144
	ds_read_b128 v[190:193], v144 offset:7168
	global_load_lds_dwordx4 v138, s[14:15]
	s_add_i32 m0, s26, 0xe000
	s_nop 0
	global_load_lds_dwordx4 v140, s[14:15]
	s_waitcnt lgkmcnt(8)
	s_barrier
	s_waitcnt lgkmcnt(0)
	s_setprio 1
	v_mfma_f32_16x16x32_bf16 v[128:131], v[146:149], v[162:165], v[128:131]
	v_mfma_f32_16x16x32_bf16 v[128:131], v[150:153], v[166:169], v[128:131]
	v_mfma_f32_16x16x32_bf16 v[120:123], v[150:153], v[174:177], v[120:123]
	v_mfma_f32_16x16x32_bf16 v[120:123], v[146:149], v[170:173], v[120:123]
	v_mfma_f32_16x16x32_bf16 v[104:107], v[146:149], v[178:181], v[104:107]
	v_mfma_f32_16x16x32_bf16 v[104:107], v[150:153], v[182:185], v[104:107]
	v_mfma_f32_16x16x32_bf16 v[88:91], v[150:153], v[190:193], v[88:91]
	v_mfma_f32_16x16x32_bf16 v[88:91], v[146:149], v[186:189], v[88:91]
	v_mfma_f32_16x16x32_bf16 v[84:87], v[154:157], v[186:189], v[84:87]
	v_mfma_f32_16x16x32_bf16 v[84:87], v[158:161], v[190:193], v[84:87]
	v_mfma_f32_16x16x32_bf16 v[100:103], v[158:161], v[182:185], v[100:103]
	v_mfma_f32_16x16x32_bf16 v[100:103], v[154:157], v[178:181], v[100:103]
	v_mfma_f32_16x16x32_bf16 v[116:119], v[154:157], v[170:173], v[116:119]
	v_mfma_f32_16x16x32_bf16 v[116:119], v[158:161], v[174:177], v[116:119]
	v_mfma_f32_16x16x32_bf16 v[124:127], v[158:161], v[166:169], v[124:127]
	s_barrier
	v_mfma_f32_16x16x32_bf16 v[124:127], v[154:157], v[162:165], v[124:127]
	s_setprio 0
	s_add_i32 s44, 0, 0x14000
	s_add_i32 s41, s41, s25
	v_add_u32_e32 v145, s44, v142
	v_lshl_add_u64 v[212:213], s[16:17], 0, v[2:3]
	s_mov_b32 m0, s41
	ds_read_b128 v[194:197], v145
	ds_read_b128 v[200:203], v145 offset:1024
	ds_read_b128 v[204:207], v145 offset:2048
	ds_read_b128 v[208:211], v145 offset:3072
	global_load_lds_dwordx4 v[212:213], off
	v_lshl_add_u64 v[214:215], s[16:17], 0, v[132:133]
	s_add_i32 m0, s41, 0x2000
	s_nop 0
	global_load_lds_dwordx4 v[214:215], off
	s_barrier
	s_waitcnt lgkmcnt(0)
	s_setprio 1
	v_mfma_f32_16x16x32_bf16 v[112:115], v[194:197], v[162:165], v[112:115]
	v_mfma_f32_16x16x32_bf16 v[112:115], v[200:203], v[166:169], v[112:115]
	v_mfma_f32_16x16x32_bf16 v[96:99], v[200:203], v[174:177], v[96:99]
	v_mfma_f32_16x16x32_bf16 v[96:99], v[194:197], v[170:173], v[96:99]
	v_mfma_f32_16x16x32_bf16 v[80:83], v[194:197], v[178:181], v[80:83]
	v_mfma_f32_16x16x32_bf16 v[80:83], v[200:203], v[182:185], v[80:83]
	v_mfma_f32_16x16x32_bf16 v[72:75], v[200:203], v[190:193], v[72:75]
	v_mfma_f32_16x16x32_bf16 v[72:75], v[194:197], v[186:189], v[72:75]
	v_mfma_f32_16x16x32_bf16 v[68:71], v[204:207], v[186:189], v[68:71]
	v_mfma_f32_16x16x32_bf16 v[68:71], v[208:211], v[190:193], v[68:71]
	v_mfma_f32_16x16x32_bf16 v[76:79], v[208:211], v[182:185], v[76:79]
	v_mfma_f32_16x16x32_bf16 v[76:79], v[204:207], v[178:181], v[76:79]
	v_mfma_f32_16x16x32_bf16 v[92:95], v[204:207], v[170:173], v[92:95]
	v_mfma_f32_16x16x32_bf16 v[92:95], v[208:211], v[174:177], v[92:95]
	v_mfma_f32_16x16x32_bf16 v[108:111], v[208:211], v[166:169], v[108:111]
	s_barrier
	v_mfma_f32_16x16x32_bf16 v[108:111], v[204:207], v[162:165], v[108:111]
	s_setprio 0
	s_mov_b32 m0, s26
	v_lshl_add_u64 v[216:217], s[18:19], 0, v[136:137]
	ds_read_b128 v[162:165], v144 offset:16384
	ds_read_b128 v[166:169], v144 offset:17408
	ds_read_b128 v[170:173], v144 offset:18432
	ds_read_b128 v[174:177], v144 offset:19456
	ds_read_b128 v[178:181], v144 offset:20480
	ds_read_b128 v[182:185], v144 offset:21504
	ds_read_b128 v[186:189], v144 offset:22528
	ds_read_b128 v[190:193], v144 offset:23552
	global_load_lds_dwordx4 v[216:217], off
	v_lshl_add_u64 v[218:219], s[18:19], 0, v[134:135]
	s_mov_b32 m0, s27
	s_nop 0
	global_load_lds_dwordx4 v[218:219], off
	s_waitcnt vmcnt(10)
	s_barrier
	s_waitcnt lgkmcnt(0)
	s_setprio 1
	v_mfma_f32_16x16x32_bf16 v[64:67], v[146:149], v[162:165], v[64:67]
	v_mfma_f32_16x16x32_bf16 v[64:67], v[150:153], v[166:169], v[64:67]
	v_mfma_f32_16x16x32_bf16 v[56:59], v[150:153], v[174:177], v[56:59]
	v_mfma_f32_16x16x32_bf16 v[56:59], v[146:149], v[170:173], v[56:59]
	v_mfma_f32_16x16x32_bf16 v[40:43], v[146:149], v[178:181], v[40:43]
	v_mfma_f32_16x16x32_bf16 v[40:43], v[150:153], v[182:185], v[40:43]
	v_mfma_f32_16x16x32_bf16 v[24:27], v[150:153], v[190:193], v[24:27]
	v_mfma_f32_16x16x32_bf16 v[24:27], v[146:149], v[186:189], v[24:27]
	v_mfma_f32_16x16x32_bf16 v[20:23], v[154:157], v[186:189], v[20:23]
	v_mfma_f32_16x16x32_bf16 v[20:23], v[158:161], v[190:193], v[20:23]
	v_mfma_f32_16x16x32_bf16 v[36:39], v[158:161], v[182:185], v[36:39]
	v_mfma_f32_16x16x32_bf16 v[36:39], v[154:157], v[178:181], v[36:39]
	v_mfma_f32_16x16x32_bf16 v[52:55], v[154:157], v[170:173], v[52:55]
	v_mfma_f32_16x16x32_bf16 v[52:55], v[158:161], v[174:177], v[52:55]
	v_mfma_f32_16x16x32_bf16 v[60:63], v[158:161], v[166:169], v[60:63]
	s_barrier
	v_mfma_f32_16x16x32_bf16 v[60:63], v[154:157], v[162:165], v[60:63]
	s_setprio 0
	s_add_u32 s42, s16, 0x8000
	s_addc_u32 s43, s17, 0
	s_add_i32 s41, s44, s25
	s_mov_b32 m0, s41
	s_nop 0
	global_load_lds_dwordx4 v2, s[42:43]
	s_add_i32 m0, s41, 0x2000
	s_nop 0
	global_load_lds_dwordx4 v132, s[42:43]
	s_add_i32 s41, 0, 0x18000
	v_add_u32_e32 v145, s41, v142
	ds_read_b128 v[146:149], v145
	ds_read_b128 v[150:153], v145 offset:1024
	ds_read_b128 v[154:157], v145 offset:2048
	ds_read_b128 v[158:161], v145 offset:3072
	s_waitcnt vmcnt(6)
	s_barrier
	s_setprio 1
	v_mfma_f32_16x16x32_bf16 v[48:51], v[194:197], v[162:165], v[48:51]
	v_mfma_f32_16x16x32_bf16 v[48:51], v[200:203], v[166:169], v[48:51]
	v_mfma_f32_16x16x32_bf16 v[32:35], v[200:203], v[174:177], v[32:35]
	v_mfma_f32_16x16x32_bf16 v[32:35], v[194:197], v[170:173], v[32:35]
	v_mfma_f32_16x16x32_bf16 v[16:19], v[194:197], v[178:181], v[16:19]
	v_mfma_f32_16x16x32_bf16 v[16:19], v[200:203], v[182:185], v[16:19]
	v_mfma_f32_16x16x32_bf16 v[8:11], v[200:203], v[190:193], v[8:11]
	v_mfma_f32_16x16x32_bf16 v[8:11], v[194:197], v[186:189], v[8:11]
	v_mfma_f32_16x16x32_bf16 v[4:7], v[204:207], v[186:189], v[4:7]
	v_mfma_f32_16x16x32_bf16 v[4:7], v[208:211], v[190:193], v[4:7]
	v_mfma_f32_16x16x32_bf16 v[12:15], v[208:211], v[182:185], v[12:15]
	v_mfma_f32_16x16x32_bf16 v[12:15], v[204:207], v[178:181], v[12:15]
	v_mfma_f32_16x16x32_bf16 v[28:31], v[204:207], v[170:173], v[28:31]
	v_mfma_f32_16x16x32_bf16 v[28:31], v[208:211], v[174:177], v[28:31]
	v_mfma_f32_16x16x32_bf16 v[44:47], v[208:211], v[166:169], v[44:47]
	s_barrier
	v_mfma_f32_16x16x32_bf16 v[44:47], v[204:207], v[162:165], v[44:47]
	s_setprio 0
	s_add_u32 s18, s18, 0x20000
	s_addc_u32 s19, s19, 0
	s_mov_b32 m0, s28
	ds_read_b128 v[162:165], v144 offset:32768
	ds_read_b128 v[166:169], v144 offset:33792
	ds_read_b128 v[170:173], v144 offset:34816
	ds_read_b128 v[174:177], v144 offset:35840
	ds_read_b128 v[178:181], v144 offset:36864
	ds_read_b128 v[182:185], v144 offset:37888
	ds_read_b128 v[186:189], v144 offset:38912
	ds_read_b128 v[190:193], v144 offset:39936
	global_load_lds_dwordx4 v136, s[18:19]
	s_mov_b32 m0, s29
	s_nop 0
	global_load_lds_dwordx4 v134, s[18:19]
	s_waitcnt lgkmcnt(8)
	s_barrier
	s_waitcnt lgkmcnt(0)
	s_setprio 1
	v_mfma_f32_16x16x32_bf16 v[128:131], v[146:149], v[162:165], v[128:131]
	v_mfma_f32_16x16x32_bf16 v[128:131], v[150:153], v[166:169], v[128:131]
	v_mfma_f32_16x16x32_bf16 v[120:123], v[150:153], v[174:177], v[120:123]
	v_mfma_f32_16x16x32_bf16 v[120:123], v[146:149], v[170:173], v[120:123]
	v_mfma_f32_16x16x32_bf16 v[104:107], v[146:149], v[178:181], v[104:107]
	v_mfma_f32_16x16x32_bf16 v[104:107], v[150:153], v[182:185], v[104:107]
	v_mfma_f32_16x16x32_bf16 v[88:91], v[150:153], v[190:193], v[88:91]
	v_mfma_f32_16x16x32_bf16 v[88:91], v[146:149], v[186:189], v[88:91]
	v_mfma_f32_16x16x32_bf16 v[84:87], v[154:157], v[186:189], v[84:87]
	v_mfma_f32_16x16x32_bf16 v[84:87], v[158:161], v[190:193], v[84:87]
	v_mfma_f32_16x16x32_bf16 v[100:103], v[158:161], v[182:185], v[100:103]
	v_mfma_f32_16x16x32_bf16 v[100:103], v[154:157], v[178:181], v[100:103]
	v_mfma_f32_16x16x32_bf16 v[116:119], v[154:157], v[170:173], v[116:119]
	v_mfma_f32_16x16x32_bf16 v[116:119], v[158:161], v[174:177], v[116:119]
	v_mfma_f32_16x16x32_bf16 v[124:127], v[158:161], v[166:169], v[124:127]
	s_barrier
	v_mfma_f32_16x16x32_bf16 v[124:127], v[154:157], v[162:165], v[124:127]
	s_setprio 0
	s_add_i32 s18, 0, 0x1c000
	s_add_i32 s19, s41, s25
	v_add_u32_e32 v145, s18, v142
	v_lshl_add_u64 v[212:213], v[212:213], 0, s[2:3]
	s_mov_b32 m0, s19
	ds_read_b128 v[194:197], v145
	ds_read_b128 v[200:203], v145 offset:1024
	ds_read_b128 v[204:207], v145 offset:2048
	ds_read_b128 v[208:211], v145 offset:3072
	global_load_lds_dwordx4 v[212:213], off
	v_lshl_add_u64 v[212:213], v[214:215], 0, s[2:3]
	s_add_i32 m0, s19, 0x2000
	s_nop 0
	global_load_lds_dwordx4 v[212:213], off
	s_barrier
	s_waitcnt lgkmcnt(0)
	s_setprio 1
	v_mfma_f32_16x16x32_bf16 v[112:115], v[194:197], v[162:165], v[112:115]
	v_mfma_f32_16x16x32_bf16 v[112:115], v[200:203], v[166:169], v[112:115]
	v_mfma_f32_16x16x32_bf16 v[96:99], v[200:203], v[174:177], v[96:99]
	v_mfma_f32_16x16x32_bf16 v[96:99], v[194:197], v[170:173], v[96:99]
	v_mfma_f32_16x16x32_bf16 v[80:83], v[194:197], v[178:181], v[80:83]
	v_mfma_f32_16x16x32_bf16 v[80:83], v[200:203], v[182:185], v[80:83]
	v_mfma_f32_16x16x32_bf16 v[72:75], v[200:203], v[190:193], v[72:75]
	v_mfma_f32_16x16x32_bf16 v[72:75], v[194:197], v[186:189], v[72:75]
	v_mfma_f32_16x16x32_bf16 v[68:71], v[204:207], v[186:189], v[68:71]
	v_mfma_f32_16x16x32_bf16 v[68:71], v[208:211], v[190:193], v[68:71]
	v_mfma_f32_16x16x32_bf16 v[76:79], v[208:211], v[182:185], v[76:79]
	v_mfma_f32_16x16x32_bf16 v[76:79], v[204:207], v[178:181], v[76:79]
	v_mfma_f32_16x16x32_bf16 v[92:95], v[204:207], v[170:173], v[92:95]
	v_mfma_f32_16x16x32_bf16 v[92:95], v[208:211], v[174:177], v[92:95]
	v_mfma_f32_16x16x32_bf16 v[108:111], v[208:211], v[166:169], v[108:111]
	s_barrier
	v_mfma_f32_16x16x32_bf16 v[108:111], v[204:207], v[162:165], v[108:111]
	s_setprio 0
	s_mov_b32 m0, s30
	v_lshl_add_u64 v[212:213], v[216:217], 0, s[2:3]
	ds_read_b128 v[162:165], v144 offset:49152
	ds_read_b128 v[166:169], v144 offset:50176
	ds_read_b128 v[170:173], v144 offset:51200
	ds_read_b128 v[174:177], v144 offset:52224
	ds_read_b128 v[178:181], v144 offset:53248
	ds_read_b128 v[182:185], v144 offset:54272
	ds_read_b128 v[186:189], v144 offset:55296
	ds_read_b128 v[190:193], v144 offset:56320
	global_load_lds_dwordx4 v[212:213], off
	v_lshl_add_u64 v[212:213], v[218:219], 0, s[2:3]
	s_mov_b32 m0, s31
	s_nop 0
	global_load_lds_dwordx4 v[212:213], off
	s_barrier
	s_waitcnt lgkmcnt(0)
	s_setprio 1
	v_mfma_f32_16x16x32_bf16 v[64:67], v[146:149], v[162:165], v[64:67]
	v_mfma_f32_16x16x32_bf16 v[64:67], v[150:153], v[166:169], v[64:67]
	v_mfma_f32_16x16x32_bf16 v[56:59], v[150:153], v[174:177], v[56:59]
	v_mfma_f32_16x16x32_bf16 v[56:59], v[146:149], v[170:173], v[56:59]
	v_mfma_f32_16x16x32_bf16 v[40:43], v[146:149], v[178:181], v[40:43]
	v_mfma_f32_16x16x32_bf16 v[40:43], v[150:153], v[182:185], v[40:43]
	v_mfma_f32_16x16x32_bf16 v[24:27], v[150:153], v[190:193], v[24:27]
	v_mfma_f32_16x16x32_bf16 v[24:27], v[146:149], v[186:189], v[24:27]
	v_mfma_f32_16x16x32_bf16 v[20:23], v[154:157], v[186:189], v[20:23]
	v_mfma_f32_16x16x32_bf16 v[20:23], v[158:161], v[190:193], v[20:23]
	v_mfma_f32_16x16x32_bf16 v[36:39], v[158:161], v[182:185], v[36:39]
	v_mfma_f32_16x16x32_bf16 v[36:39], v[154:157], v[178:181], v[36:39]
	v_mfma_f32_16x16x32_bf16 v[52:55], v[154:157], v[170:173], v[52:55]
	v_mfma_f32_16x16x32_bf16 v[52:55], v[158:161], v[174:177], v[52:55]
	v_mfma_f32_16x16x32_bf16 v[60:63], v[158:161], v[166:169], v[60:63]
	s_barrier
	v_mfma_f32_16x16x32_bf16 v[60:63], v[154:157], v[162:165], v[60:63]
	s_setprio 0
	s_add_u32 s16, s16, 0x8080
	s_addc_u32 s17, s17, 0
	s_add_i32 s18, s18, s25
	s_mov_b32 m0, s18
	s_nop 0
	global_load_lds_dwordx4 v2, s[16:17]
	s_add_i32 m0, s18, 0x2000
	s_nop 0
	global_load_lds_dwordx4 v132, s[16:17]
	s_waitcnt vmcnt(6)
	s_barrier
	s_setprio 1
	v_mfma_f32_16x16x32_bf16 v[48:51], v[194:197], v[162:165], v[48:51]
	v_mfma_f32_16x16x32_bf16 v[48:51], v[200:203], v[166:169], v[48:51]
	v_mfma_f32_16x16x32_bf16 v[32:35], v[200:203], v[174:177], v[32:35]
	v_mfma_f32_16x16x32_bf16 v[32:35], v[194:197], v[170:173], v[32:35]
	v_mfma_f32_16x16x32_bf16 v[16:19], v[194:197], v[178:181], v[16:19]
	v_mfma_f32_16x16x32_bf16 v[16:19], v[200:203], v[182:185], v[16:19]
	v_mfma_f32_16x16x32_bf16 v[8:11], v[200:203], v[190:193], v[8:11]
	v_mfma_f32_16x16x32_bf16 v[8:11], v[194:197], v[186:189], v[8:11]
	v_mfma_f32_16x16x32_bf16 v[4:7], v[204:207], v[186:189], v[4:7]
	v_mfma_f32_16x16x32_bf16 v[4:7], v[208:211], v[190:193], v[4:7]
	v_mfma_f32_16x16x32_bf16 v[12:15], v[208:211], v[182:185], v[12:15]
	v_mfma_f32_16x16x32_bf16 v[12:15], v[204:207], v[178:181], v[12:15]
	v_mfma_f32_16x16x32_bf16 v[28:31], v[204:207], v[170:173], v[28:31]
	v_mfma_f32_16x16x32_bf16 v[28:31], v[208:211], v[174:177], v[28:31]
	v_mfma_f32_16x16x32_bf16 v[44:47], v[208:211], v[166:169], v[44:47]
	s_barrier
	v_mfma_f32_16x16x32_bf16 v[44:47], v[204:207], v[162:165], v[44:47]
	s_setprio 0
	s_add_i32 s40, s40, 2
	s_add_u32 s14, s14, 0x100
	s_addc_u32 s15, s15, 0
	s_add_u32 s38, s38, 0x100
	s_addc_u32 s39, s39, 0
	s_cmp_gt_u32 s40, 5
	s_cbranch_scc0 .LBB0_236
	v_lshl_add_u32 v146, s35, 8, v1
	v_lshl_or_b32 v148, s34, 8, v143
	v_ashrrev_i32_e32 v147, 31, v146
	v_ashrrev_i32_e32 v149, 31, v148
	v_lshlrev_b64 v[150:151], 12, v[146:147]
	v_lshl_add_u64 v[150:151], s[4:5], 0, v[150:151]
	v_lshlrev_b64 v[148:149], 1, v[148:149]
	v_lshl_add_u64 v[150:151], v[150:151], 0, v[148:149]
	s_mov_b32 s7, 0x80000
	s_mov_b64 s[14:15], 0x80000
	v_cvt_pk_bf16_f32 v64, v64, v65
	v_cvt_pk_bf16_f32 v65, v66, v67
	v_cvt_pk_bf16_f32 v66, v60, v61
	v_add_co_u32_e32 v60, vcc, s7, v150
	v_cvt_pk_bf16_f32 v72, v72, v73
	v_cvt_pk_bf16_f32 v73, v74, v75
	v_cvt_pk_bf16_f32 v74, v68, v69
	v_lshl_add_u64 v[68:69], v[150:151], 0, s[14:15]
	v_addc_co_u32_e32 v61, vcc, 0, v151, vcc
	v_cvt_pk_bf16_f32 v48, v48, v49
	v_cvt_pk_bf16_f32 v49, v50, v51
	v_cvt_pk_bf16_f32 v50, v44, v45
	v_cvt_pk_bf16_f32 v51, v46, v47
	s_mov_b32 s7, 0x90000
	v_cvt_pk_bf16_f32 v112, v112, v113
	v_cvt_pk_bf16_f32 v113, v114, v115
	v_cvt_pk_bf16_f32 v114, v108, v109
	v_or_b32_e32 v108, 16, v146
	global_store_dwordx4 v[68:69], v[48:51], off offset:64
	s_mov_b64 s[14:15], 0x90000
	v_ashrrev_i32_e32 v109, 31, v108
	v_add_co_u32_e32 v50, vcc, s7, v150
	v_cvt_pk_bf16_f32 v96, v96, v97
	v_cvt_pk_bf16_f32 v97, v98, v99
	v_cvt_pk_bf16_f32 v98, v92, v93
	v_or_b32_e32 v92, 32, v146
	v_lshl_add_u64 v[48:49], v[150:151], 0, s[14:15]
	v_addc_co_u32_e32 v51, vcc, 0, v151, vcc
	v_cvt_pk_bf16_f32 v32, v32, v33
	v_cvt_pk_bf16_f32 v33, v34, v35
	v_cvt_pk_bf16_f32 v34, v28, v29
	v_cvt_pk_bf16_f32 v35, v30, v31
	s_mov_b32 s7, 0xa0000
	v_lshlrev_b64 v[108:109], 12, v[108:109]
	v_ashrrev_i32_e32 v93, 31, v92
	v_cvt_pk_bf16_f32 v80, v80, v81
	v_cvt_pk_bf16_f32 v81, v82, v83
	v_cvt_pk_bf16_f32 v82, v76, v77
	v_or_b32_e32 v76, 48, v146
	global_store_dwordx4 v[48:49], v[32:35], off offset:64
	s_mov_b64 s[14:15], 0xa0000
	v_cvt_pk_bf16_f32 v115, v110, v111
	v_add_co_u32_e32 v34, vcc, s7, v150
	v_lshl_add_u64 v[108:109], s[4:5], 0, v[108:109]
	v_lshlrev_b64 v[92:93], 12, v[92:93]
	v_ashrrev_i32_e32 v77, 31, v76
	v_lshl_add_u64 v[32:33], v[150:151], 0, s[14:15]
	v_addc_co_u32_e32 v35, vcc, 0, v151, vcc
	v_cvt_pk_bf16_f32 v16, v16, v17
	v_cvt_pk_bf16_f32 v17, v18, v19
	v_cvt_pk_bf16_f32 v18, v12, v13
	v_cvt_pk_bf16_f32 v19, v14, v15
	s_mov_b32 s7, 0xb0000
	global_store_dwordx4 v[150:151], v[112:115], off offset:64
	v_cvt_pk_bf16_f32 v99, v94, v95
	v_lshl_add_u64 v[92:93], s[4:5], 0, v[92:93]
	v_lshl_add_u64 v[112:113], v[108:109], 0, v[148:149]
	v_lshlrev_b64 v[76:77], 12, v[76:77]
	global_store_dwordx4 v[32:33], v[16:19], off offset:64
	global_store_dwordx4 v[112:113], v[96:99], off offset:64
	v_cvt_pk_bf16_f32 v83, v78, v79
	v_add_co_u32_e32 v18, vcc, s7, v150
	v_lshl_add_u64 v[96:97], v[92:93], 0, v[148:149]
	v_lshl_add_u64 v[76:77], s[4:5], 0, v[76:77]
	s_mov_b64 s[14:15], 0xb0000
	v_addc_co_u32_e32 v19, vcc, 0, v151, vcc
	v_cvt_pk_bf16_f32 v128, v128, v129
	v_cvt_pk_bf16_f32 v129, v130, v131
	v_cvt_pk_bf16_f32 v130, v124, v125
	v_cvt_pk_bf16_f32 v131, v126, v127
	v_cvt_pk_bf16_f32 v108, v120, v121
	v_cvt_pk_bf16_f32 v109, v122, v123
	v_cvt_pk_bf16_f32 v110, v116, v117
	v_cvt_pk_bf16_f32 v111, v118, v119
	v_cvt_pk_bf16_f32 v92, v104, v105
	v_cvt_pk_bf16_f32 v93, v106, v107
	v_cvt_pk_bf16_f32 v94, v100, v101
	v_cvt_pk_bf16_f32 v95, v102, v103
	global_store_dwordx4 v[96:97], v[80:83], off offset:64
	v_cvt_pk_bf16_f32 v78, v84, v85
	v_cvt_pk_bf16_f32 v79, v86, v87
	v_lshl_add_u64 v[80:81], v[76:77], 0, v[148:149]
	v_cvt_pk_bf16_f32 v76, v88, v89
	v_cvt_pk_bf16_f32 v77, v90, v91
	v_cvt_pk_bf16_f32 v75, v70, v71
	v_cvt_pk_bf16_f32 v67, v62, v63
	v_cvt_pk_bf16_f32 v44, v56, v57
	v_cvt_pk_bf16_f32 v45, v58, v59
	v_cvt_pk_bf16_f32 v46, v52, v53
	v_cvt_pk_bf16_f32 v47, v54, v55
	v_cvt_pk_bf16_f32 v28, v40, v41
	v_cvt_pk_bf16_f32 v29, v42, v43
	v_cvt_pk_bf16_f32 v30, v36, v37
	v_cvt_pk_bf16_f32 v31, v38, v39
	v_lshl_add_u64 v[16:17], v[150:151], 0, s[14:15]
	v_cvt_pk_bf16_f32 v12, v24, v25
	v_cvt_pk_bf16_f32 v13, v26, v27
	v_cvt_pk_bf16_f32 v14, v20, v21
	v_cvt_pk_bf16_f32 v15, v22, v23
	v_cvt_pk_bf16_f32 v8, v8, v9
	v_cvt_pk_bf16_f32 v9, v10, v11
	v_cvt_pk_bf16_f32 v10, v4, v5
	v_cvt_pk_bf16_f32 v11, v6, v7
	s_and_b64 vcc, exec, s[0:1]
	s_mov_b32 s34, s6
	s_mov_b32 s35, s8
	s_mov_b64 s[16:17], s[12:13]
	s_mov_b64 s[14:15], s[10:11]
	global_store_dwordx4 v[150:151], v[128:131], off
	global_store_dwordx4 v[112:113], v[108:111], off
	global_store_dwordx4 v[96:97], v[92:95], off
	global_store_dwordx4 v[80:81], v[76:79], off
	global_store_dwordx4 v[80:81], v[72:75], off offset:64
	global_store_dwordx4 v[60:61], v[64:67], off
	global_store_dwordx4 v[50:51], v[44:47], off
	global_store_dwordx4 v[34:35], v[28:31], off
	global_store_dwordx4 v[18:19], v[12:15], off
	global_store_dwordx4 v[16:17], v[8:11], off offset:64
	s_cbranch_vccz .LBB0_233
	s_waitcnt vmcnt(0)
	s_cmpk_gt_u32 s20, 0xff
	s_cbranch_scc1 .LBB0_240
	s_barrier

.LBB0_816:
	s_add_u32 s18, s16, 0x100
	s_addc_u32 s19, s17, 0
	s_cmpk_eq_i32 s14, 0x2e00
	s_cselect_b32 s23, s1, s19
	s_cselect_b32 s22, s0, s18
	s_cselect_b32 s21, s7, s42
	s_cselect_b32 s20, s6, s41
	s_add_i32 s33, 0, 0x10000
	v_add_u32_e32 v2, s33, v200
	ds_read_b128 v[62:65], v2
	ds_read_b128 v[74:77], v2 offset:1024
	ds_read_b128 v[82:85], v2 offset:2048
	ds_read_b128 v[94:97], v2 offset:3072
	s_add_i32 m0, s30, 0xc000
	ds_read_b128 v[106:109], v202
	ds_read_b128 v[118:121], v202 offset:1024
	ds_read_b128 v[130:133], v202 offset:2048
	ds_read_b128 v[142:145], v202 offset:3072
	ds_read_b128 v[150:153], v202 offset:4096
	ds_read_b128 v[162:165], v202 offset:5120
	ds_read_b128 v[174:177], v202 offset:6144
	ds_read_b128 v[178:181], v202 offset:7168
	global_load_lds_dwordx4 v212, s[16:17]
	s_add_i32 m0, s30, 0xe000
	s_nop 0
	global_load_lds_dwordx4 v214, s[16:17]
	s_waitcnt lgkmcnt(8)
	s_barrier
	s_waitcnt lgkmcnt(0)
	s_setprio 1
	v_mfma_f32_16x16x32_bf16 v[170:173], v[62:65], v[106:109], v[170:173]
	v_mfma_f32_16x16x32_bf16 v[170:173], v[74:77], v[118:121], v[170:173]
	v_mfma_f32_16x16x32_bf16 v[146:149], v[74:77], v[142:145], v[146:149]
	v_mfma_f32_16x16x32_bf16 v[146:149], v[62:65], v[130:133], v[146:149]
	v_mfma_f32_16x16x32_bf16 v[122:125], v[62:65], v[150:153], v[122:125]
	v_mfma_f32_16x16x32_bf16 v[122:125], v[74:77], v[162:165], v[122:125]
	v_mfma_f32_16x16x32_bf16 v[98:101], v[74:77], v[178:181], v[98:101]
	v_mfma_f32_16x16x32_bf16 v[98:101], v[62:65], v[174:177], v[98:101]
	v_mfma_f32_16x16x32_bf16 v[90:93], v[82:85], v[174:177], v[90:93]
	v_mfma_f32_16x16x32_bf16 v[90:93], v[94:97], v[178:181], v[90:93]
	v_mfma_f32_16x16x32_bf16 v[114:117], v[94:97], v[162:165], v[114:117]
	v_mfma_f32_16x16x32_bf16 v[114:117], v[82:85], v[150:153], v[114:117]
	v_mfma_f32_16x16x32_bf16 v[138:141], v[82:85], v[130:133], v[138:141]
	v_mfma_f32_16x16x32_bf16 v[138:141], v[94:97], v[142:145], v[138:141]
	v_mfma_f32_16x16x32_bf16 v[166:169], v[94:97], v[118:121], v[166:169]
	s_barrier
	v_mfma_f32_16x16x32_bf16 v[166:169], v[82:85], v[106:109], v[166:169]
	s_setprio 0
	s_add_i32 s44, 0, 0x14000
	s_add_i32 s16, s33, s29
	v_add_u32_e32 v2, s44, v200
	v_lshl_add_u64 v[226:227], s[20:21], 0, v[208:209]
	s_mov_b32 m0, s16
	ds_read_b128 v[182:185], v2
	ds_read_b128 v[186:189], v2 offset:1024
	ds_read_b128 v[190:193], v2 offset:2048
	ds_read_b128 v[194:197], v2 offset:3072
	global_load_lds_dwordx4 v[226:227], off
	v_lshl_add_u64 v[228:229], s[20:21], 0, v[204:205]
	s_add_i32 m0, s16, 0x2000
	s_nop 0
	global_load_lds_dwordx4 v[228:229], off
	s_barrier
	s_waitcnt lgkmcnt(0)
	s_setprio 1
	v_mfma_f32_16x16x32_bf16 v[158:161], v[182:185], v[106:109], v[158:161]
	v_mfma_f32_16x16x32_bf16 v[158:161], v[186:189], v[118:121], v[158:161]
	v_mfma_f32_16x16x32_bf16 v[106:109], v[190:193], v[106:109], v[154:157]
	v_mfma_f32_16x16x32_bf16 v[106:109], v[194:197], v[118:121], v[106:109]
	v_mfma_f32_16x16x32_bf16 v[126:129], v[190:193], v[130:133], v[126:129]
	v_mfma_f32_16x16x32_bf16 v[126:129], v[194:197], v[142:145], v[126:129]
	v_mfma_f32_16x16x32_bf16 v[110:113], v[182:185], v[150:153], v[110:113]
	v_mfma_f32_16x16x32_bf16 v[110:113], v[186:189], v[162:165], v[110:113]
	v_mfma_f32_16x16x32_bf16 v[102:105], v[190:193], v[150:153], v[102:105]
	v_mfma_f32_16x16x32_bf16 v[102:105], v[194:197], v[162:165], v[102:105]
	v_mfma_f32_16x16x32_bf16 v[86:89], v[182:185], v[174:177], v[86:89]
	v_mfma_f32_16x16x32_bf16 v[86:89], v[186:189], v[178:181], v[86:89]
	v_mfma_f32_16x16x32_bf16 v[78:81], v[190:193], v[174:177], v[78:81]
	v_mfma_f32_16x16x32_bf16 v[78:81], v[194:197], v[178:181], v[78:81]
	v_mfma_f32_16x16x32_bf16 v[118:121], v[182:185], v[130:133], v[134:137]
	s_barrier
	v_mfma_f32_16x16x32_bf16 v[118:121], v[186:189], v[142:145], v[118:121]
	s_setprio 0
	s_mov_b32 m0, s30
	v_lshl_add_u64 v[230:231], s[22:23], 0, v[210:211]
	ds_read_b128 v[130:133], v202 offset:16384
	ds_read_b128 v[134:137], v202 offset:17408
	ds_read_b128 v[142:145], v202 offset:18432
	ds_read_b128 v[150:153], v202 offset:19456
	ds_read_b128 v[154:157], v202 offset:20480
	ds_read_b128 v[162:165], v202 offset:21504
	ds_read_b128 v[174:177], v202 offset:22528
	ds_read_b128 v[178:181], v202 offset:23552
	global_load_lds_dwordx4 v[230:231], off
	v_lshl_add_u64 v[232:233], s[22:23], 0, v[206:207]
	s_mov_b32 m0, s31
	s_nop 0
	global_load_lds_dwordx4 v[232:233], off
	s_waitcnt vmcnt(10)
	s_barrier
	s_waitcnt lgkmcnt(0)
	s_setprio 1
	v_mfma_f32_16x16x32_bf16 v[70:73], v[62:65], v[130:133], v[70:73]
	v_mfma_f32_16x16x32_bf16 v[70:73], v[74:77], v[134:137], v[70:73]
	v_mfma_f32_16x16x32_bf16 v[50:53], v[74:77], v[150:153], v[50:53]
	v_mfma_f32_16x16x32_bf16 v[50:53], v[62:65], v[142:145], v[50:53]
	v_mfma_f32_16x16x32_bf16 v[34:37], v[62:65], v[154:157], v[34:37]
	v_mfma_f32_16x16x32_bf16 v[34:37], v[74:77], v[162:165], v[34:37]
	v_mfma_f32_16x16x32_bf16 v[18:21], v[74:77], v[178:181], v[18:21]
	v_mfma_f32_16x16x32_bf16 v[18:21], v[62:65], v[174:177], v[18:21]
	v_mfma_f32_16x16x32_bf16 v[14:17], v[82:85], v[174:177], v[14:17]
	v_mfma_f32_16x16x32_bf16 v[14:17], v[94:97], v[178:181], v[14:17]
	v_mfma_f32_16x16x32_bf16 v[30:33], v[94:97], v[162:165], v[30:33]
	v_mfma_f32_16x16x32_bf16 v[30:33], v[82:85], v[154:157], v[30:33]
	v_mfma_f32_16x16x32_bf16 v[46:49], v[82:85], v[142:145], v[46:49]
	v_mfma_f32_16x16x32_bf16 v[46:49], v[94:97], v[150:153], v[46:49]
	v_mfma_f32_16x16x32_bf16 v[66:69], v[94:97], v[134:137], v[66:69]
	s_barrier
	v_mfma_f32_16x16x32_bf16 v[66:69], v[82:85], v[130:133], v[66:69]
	s_setprio 0
	s_add_u32 s16, s20, 0xc0000
	s_addc_u32 s17, s21, 0
	s_add_i32 s33, s44, s29
	s_mov_b32 m0, s33
	s_nop 0
	global_load_lds_dwordx4 v208, s[16:17]
	v_lshl_add_u64 v[4:5], s[16:17], 0, v[204:205]
	s_add_i32 m0, s33, 0x2000
	s_nop 0
	global_load_lds_dwordx4 v[4:5], off
	s_add_i32 s33, 0, 0x18000
	v_add_u32_e32 v2, s33, v200
	ds_read_b128 v[62:65], v2
	ds_read_b128 v[74:77], v2 offset:1024
	ds_read_b128 v[82:85], v2 offset:2048
	ds_read_b128 v[94:97], v2 offset:3072
	s_waitcnt vmcnt(6)
	s_barrier
	s_setprio 1
	v_mfma_f32_16x16x32_bf16 v[58:61], v[182:185], v[130:133], v[58:61]
	v_mfma_f32_16x16x32_bf16 v[58:61], v[186:189], v[134:137], v[58:61]
	v_mfma_f32_16x16x32_bf16 v[42:45], v[186:189], v[150:153], v[42:45]
	v_mfma_f32_16x16x32_bf16 v[42:45], v[182:185], v[142:145], v[42:45]
	v_mfma_f32_16x16x32_bf16 v[26:29], v[182:185], v[154:157], v[26:29]
	v_mfma_f32_16x16x32_bf16 v[26:29], v[186:189], v[162:165], v[26:29]
	v_mfma_f32_16x16x32_bf16 v[10:13], v[186:189], v[178:181], v[10:13]
	v_mfma_f32_16x16x32_bf16 v[10:13], v[182:185], v[174:177], v[10:13]
	v_mfma_f32_16x16x32_bf16 v[4:7], v[190:193], v[174:177], v[6:9]
	v_mfma_f32_16x16x32_bf16 v[4:7], v[194:197], v[178:181], v[4:7]
	v_mfma_f32_16x16x32_bf16 v[22:25], v[194:197], v[162:165], v[22:25]
	v_mfma_f32_16x16x32_bf16 v[22:25], v[190:193], v[154:157], v[22:25]
	v_mfma_f32_16x16x32_bf16 v[38:41], v[190:193], v[142:145], v[38:41]
	v_mfma_f32_16x16x32_bf16 v[38:41], v[194:197], v[150:153], v[38:41]
	v_mfma_f32_16x16x32_bf16 v[54:57], v[194:197], v[134:137], v[54:57]
	s_barrier
	v_mfma_f32_16x16x32_bf16 v[54:57], v[190:193], v[130:133], v[54:57]
	s_setprio 0
	s_add_u32 s16, s22, 0xc0000
	s_addc_u32 s17, s23, 0
	s_mov_b32 m0, s34
	v_lshl_add_u64 v[8:9], s[16:17], 0, v[210:211]
	ds_read_b128 v[130:133], v202 offset:32768
	ds_read_b128 v[134:137], v202 offset:33792
	ds_read_b128 v[142:145], v202 offset:34816
	ds_read_b128 v[150:153], v202 offset:35840
	ds_read_b128 v[162:165], v202 offset:36864
	ds_read_b128 v[174:177], v202 offset:37888
	ds_read_b128 v[178:181], v202 offset:38912
	ds_read_b128 v[182:185], v202 offset:39936
	global_load_lds_dwordx4 v[8:9], off
	v_lshl_add_u64 v[8:9], s[16:17], 0, v[206:207]
	s_mov_b32 m0, s35
	s_nop 0
	global_load_lds_dwordx4 v[8:9], off
	s_waitcnt lgkmcnt(8)
	s_barrier
	s_waitcnt lgkmcnt(0)
	s_setprio 1
	v_mfma_f32_16x16x32_bf16 v[154:157], v[62:65], v[130:133], v[170:173]
	v_mfma_f32_16x16x32_bf16 v[170:173], v[74:77], v[134:137], v[154:157]
	v_mfma_f32_16x16x32_bf16 v[154:157], v[82:85], v[130:133], v[166:169]
	v_mfma_f32_16x16x32_bf16 v[166:169], v[94:97], v[134:137], v[154:157]
	v_mfma_f32_16x16x32_bf16 v[146:149], v[62:65], v[142:145], v[146:149]
	v_mfma_f32_16x16x32_bf16 v[146:149], v[74:77], v[150:153], v[146:149]
	v_mfma_f32_16x16x32_bf16 v[138:141], v[82:85], v[142:145], v[138:141]
	v_mfma_f32_16x16x32_bf16 v[138:141], v[94:97], v[150:153], v[138:141]
	v_mfma_f32_16x16x32_bf16 v[122:125], v[62:65], v[162:165], v[122:125]
	v_mfma_f32_16x16x32_bf16 v[122:125], v[74:77], v[174:177], v[122:125]
	v_mfma_f32_16x16x32_bf16 v[114:117], v[82:85], v[162:165], v[114:117]
	v_mfma_f32_16x16x32_bf16 v[114:117], v[94:97], v[174:177], v[114:117]
	v_mfma_f32_16x16x32_bf16 v[98:101], v[62:65], v[178:181], v[98:101]
	v_mfma_f32_16x16x32_bf16 v[98:101], v[74:77], v[182:185], v[98:101]
	v_mfma_f32_16x16x32_bf16 v[90:93], v[82:85], v[178:181], v[90:93]
	s_barrier
	v_mfma_f32_16x16x32_bf16 v[90:93], v[94:97], v[182:185], v[90:93]
	s_setprio 0
	s_add_i32 s22, 0, 0x1c000
	s_add_i32 s16, s33, s29
	v_add_u32_e32 v2, s22, v200
	v_lshl_add_u64 v[8:9], v[226:227], 0, s[2:3]
	s_mov_b32 m0, s16
	ds_read_b128 v[186:189], v2
	ds_read_b128 v[190:193], v2 offset:1024
	ds_read_b128 v[194:197], v2 offset:2048
	ds_read_b128 v[220:223], v2 offset:3072
	global_load_lds_dwordx4 v[8:9], off
	v_lshl_add_u64 v[8:9], v[228:229], 0, s[2:3]
	s_add_i32 m0, s16, 0x2000
	s_nop 0
	global_load_lds_dwordx4 v[8:9], off
	s_barrier
	s_waitcnt lgkmcnt(0)
	s_setprio 1
	v_mfma_f32_16x16x32_bf16 v[154:157], v[186:189], v[130:133], v[158:161]
	v_mfma_f32_16x16x32_bf16 v[158:161], v[190:193], v[134:137], v[154:157]
	v_mfma_f32_16x16x32_bf16 v[106:109], v[194:197], v[130:133], v[106:109]
	v_mfma_f32_16x16x32_bf16 v[154:157], v[220:223], v[134:137], v[106:109]
	v_mfma_f32_16x16x32_bf16 v[106:109], v[186:189], v[142:145], v[118:121]
	v_mfma_f32_16x16x32_bf16 v[134:137], v[190:193], v[150:153], v[106:109]
	v_mfma_f32_16x16x32_bf16 v[106:109], v[194:197], v[142:145], v[126:129]
	v_mfma_f32_16x16x32_bf16 v[126:129], v[220:223], v[150:153], v[106:109]
	v_mfma_f32_16x16x32_bf16 v[106:109], v[186:189], v[162:165], v[110:113]
	v_mfma_f32_16x16x32_bf16 v[110:113], v[190:193], v[174:177], v[106:109]
	v_mfma_f32_16x16x32_bf16 v[102:105], v[194:197], v[162:165], v[102:105]
	v_mfma_f32_16x16x32_bf16 v[102:105], v[220:223], v[174:177], v[102:105]
	v_mfma_f32_16x16x32_bf16 v[86:89], v[186:189], v[178:181], v[86:89]
	v_mfma_f32_16x16x32_bf16 v[86:89], v[190:193], v[182:185], v[86:89]
	v_mfma_f32_16x16x32_bf16 v[78:81], v[194:197], v[178:181], v[78:81]
	s_barrier
	v_mfma_f32_16x16x32_bf16 v[78:81], v[220:223], v[182:185], v[78:81]
	s_setprio 0
	s_mov_b32 m0, s36
	v_lshl_add_u64 v[8:9], v[230:231], 0, s[2:3]
	ds_read_b128 v[106:109], v202 offset:49152
	ds_read_b128 v[118:121], v202 offset:50176
	ds_read_b128 v[130:133], v202 offset:51200
	ds_read_b128 v[142:145], v202 offset:52224
	ds_read_b128 v[150:153], v202 offset:53248
	ds_read_b128 v[162:165], v202 offset:54272
	ds_read_b128 v[174:177], v202 offset:55296
	ds_read_b128 v[178:181], v202 offset:56320
	global_load_lds_dwordx4 v[8:9], off
	v_lshl_add_u64 v[8:9], v[232:233], 0, s[2:3]
	s_mov_b32 m0, s37
	s_nop 0
	global_load_lds_dwordx4 v[8:9], off
	s_barrier
	s_waitcnt lgkmcnt(0)
	s_setprio 1
	v_mfma_f32_16x16x32_bf16 v[70:73], v[62:65], v[106:109], v[70:73]
	v_mfma_f32_16x16x32_bf16 v[70:73], v[74:77], v[118:121], v[70:73]
	v_mfma_f32_16x16x32_bf16 v[50:53], v[74:77], v[142:145], v[50:53]
	v_mfma_f32_16x16x32_bf16 v[50:53], v[62:65], v[130:133], v[50:53]
	v_mfma_f32_16x16x32_bf16 v[34:37], v[62:65], v[150:153], v[34:37]
	v_mfma_f32_16x16x32_bf16 v[34:37], v[74:77], v[162:165], v[34:37]
	v_mfma_f32_16x16x32_bf16 v[18:21], v[74:77], v[178:181], v[18:21]
	v_mfma_f32_16x16x32_bf16 v[18:21], v[62:65], v[174:177], v[18:21]
	v_mfma_f32_16x16x32_bf16 v[14:17], v[82:85], v[174:177], v[14:17]
	v_mfma_f32_16x16x32_bf16 v[14:17], v[94:97], v[178:181], v[14:17]
	v_mfma_f32_16x16x32_bf16 v[30:33], v[94:97], v[162:165], v[30:33]
	v_mfma_f32_16x16x32_bf16 v[30:33], v[82:85], v[150:153], v[30:33]
	v_mfma_f32_16x16x32_bf16 v[46:49], v[82:85], v[130:133], v[46:49]
	v_mfma_f32_16x16x32_bf16 v[46:49], v[94:97], v[142:145], v[46:49]
	v_mfma_f32_16x16x32_bf16 v[66:69], v[94:97], v[118:121], v[66:69]
	s_barrier
	v_mfma_f32_16x16x32_bf16 v[66:69], v[82:85], v[106:109], v[66:69]
	s_setprio 0
	s_add_u32 s16, s20, 0xc0080
	s_addc_u32 s17, s21, 0
	s_add_i32 s20, s22, s29
	v_lshl_add_u64 v[8:9], s[16:17], 0, v[208:209]
	s_mov_b32 m0, s20
	s_nop 0
	global_load_lds_dwordx4 v[8:9], off
	v_lshl_add_u64 v[8:9], s[16:17], 0, v[204:205]
	s_add_i32 m0, s20, 0x2000
	s_nop 0
	global_load_lds_dwordx4 v[8:9], off
	s_waitcnt vmcnt(6)
	s_barrier
	s_setprio 1
	v_mfma_f32_16x16x32_bf16 v[58:61], v[186:189], v[106:109], v[58:61]
	v_mfma_f32_16x16x32_bf16 v[58:61], v[190:193], v[118:121], v[58:61]
	v_mfma_f32_16x16x32_bf16 v[54:57], v[194:197], v[106:109], v[54:57]
	v_mfma_f32_16x16x32_bf16 v[54:57], v[220:223], v[118:121], v[54:57]
	v_mfma_f32_16x16x32_bf16 v[42:45], v[186:189], v[130:133], v[42:45]
	v_mfma_f32_16x16x32_bf16 v[42:45], v[190:193], v[142:145], v[42:45]
	v_mfma_f32_16x16x32_bf16 v[38:41], v[194:197], v[130:133], v[38:41]
	v_mfma_f32_16x16x32_bf16 v[38:41], v[220:223], v[142:145], v[38:41]
	v_mfma_f32_16x16x32_bf16 v[26:29], v[186:189], v[150:153], v[26:29]
	v_mfma_f32_16x16x32_bf16 v[26:29], v[190:193], v[162:165], v[26:29]
	v_mfma_f32_16x16x32_bf16 v[22:25], v[194:197], v[150:153], v[22:25]
	v_mfma_f32_16x16x32_bf16 v[22:25], v[220:223], v[162:165], v[22:25]
	v_mfma_f32_16x16x32_bf16 v[8:11], v[186:189], v[174:177], v[10:13]
	v_mfma_f32_16x16x32_bf16 v[10:13], v[190:193], v[178:181], v[8:11]
	v_mfma_f32_16x16x32_bf16 v[4:7], v[194:197], v[174:177], v[4:7]
	s_barrier
	v_mfma_f32_16x16x32_bf16 v[6:9], v[220:223], v[178:181], v[4:7]
	s_setprio 0
	s_add_u32 s14, s14, 0x200
	s_addc_u32 s15, s15, 0
	s_add_u32 s41, s41, 0x100
	s_addc_u32 s42, s42, 0
	s_cmp_gt_u32 s43, 45
	s_cbranch_scc1 .LBB0_806
	s_mov_b64 s[16:17], s[18:19]
	s_branch .LBB0_814

.LBB0_878:
	s_add_u32 s22, s20, 0xfff80080
	s_addc_u32 s23, s21, -1
	s_add_i32 s49, 0, 0x10000
	s_waitcnt vmcnt(0)
	v_add_u32_e32 v144, s49, v188
	ds_read_b128 v[132:135], v144
	ds_read_b128 v[136:139], v144 offset:1024
	ds_read_b128 v[140:143], v144 offset:2048
	ds_read_b128 v[144:147], v144 offset:3072
	s_cmp_eq_u32 s48, 28
	s_cselect_b32 s25, s15, s23
	s_cselect_b32 s24, s44, s22
	s_cselect_b32 s23, s13, s47
	s_cselect_b32 s22, s45, s46
	s_add_i32 m0, s34, 0xc000
	ds_read_b128 v[148:151], v190
	ds_read_b128 v[152:155], v190 offset:1024
	ds_read_b128 v[156:159], v190 offset:2048
	ds_read_b128 v[160:163], v190 offset:3072
	ds_read_b128 v[174:177], v190 offset:4096
	ds_read_b128 v[178:181], v190 offset:5120
	ds_read_b128 v[182:185], v190 offset:6144
	ds_read_b128 v[192:195], v190 offset:7168
	global_load_lds_dwordx4 v170, s[20:21]
	s_add_i32 m0, s34, 0xe000
	s_nop 0
	global_load_lds_dwordx4 v172, s[20:21]
	s_waitcnt lgkmcnt(8)
	s_barrier
	s_waitcnt lgkmcnt(0)
	s_setprio 1
	v_mfma_f32_16x16x32_bf16 v[128:131], v[132:135], v[148:151], v[128:131]
	v_mfma_f32_16x16x32_bf16 v[128:131], v[136:139], v[152:155], v[128:131]
	v_mfma_f32_16x16x32_bf16 v[120:123], v[136:139], v[160:163], v[120:123]
	v_mfma_f32_16x16x32_bf16 v[120:123], v[132:135], v[156:159], v[120:123]
	v_mfma_f32_16x16x32_bf16 v[96:99], v[132:135], v[174:177], v[96:99]
	v_mfma_f32_16x16x32_bf16 v[96:99], v[136:139], v[178:181], v[96:99]
	v_mfma_f32_16x16x32_bf16 v[88:91], v[136:139], v[192:195], v[88:91]
	v_mfma_f32_16x16x32_bf16 v[88:91], v[132:135], v[182:185], v[88:91]
	v_mfma_f32_16x16x32_bf16 v[84:87], v[140:143], v[182:185], v[84:87]
	v_mfma_f32_16x16x32_bf16 v[84:87], v[144:147], v[192:195], v[84:87]
	v_mfma_f32_16x16x32_bf16 v[92:95], v[144:147], v[178:181], v[92:95]
	v_mfma_f32_16x16x32_bf16 v[92:95], v[140:143], v[174:177], v[92:95]
	v_mfma_f32_16x16x32_bf16 v[116:119], v[140:143], v[156:159], v[116:119]
	v_mfma_f32_16x16x32_bf16 v[116:119], v[144:147], v[160:163], v[116:119]
	v_mfma_f32_16x16x32_bf16 v[124:127], v[144:147], v[152:155], v[124:127]
	s_barrier
	v_mfma_f32_16x16x32_bf16 v[124:127], v[140:143], v[148:151], v[124:127]
	s_setprio 0
	s_add_i32 s52, 0, 0x14000
	v_add_u32_e32 v186, s52, v188
	s_add_i32 s49, s49, s31
	ds_read_b128 v[200:203], v186
	ds_read_b128 v[204:207], v186 offset:1024
	ds_read_b128 v[208:211], v186 offset:2048
	ds_read_b128 v[212:215], v186 offset:3072
	v_lshl_add_u64 v[186:187], s[22:23], 0, v[2:3]
	s_mov_b32 m0, s49
	v_lshl_add_u64 v[196:197], s[22:23], 0, v[164:165]
	global_load_lds_dwordx4 v[186:187], off
	s_add_i32 m0, s49, 0x2000
	s_nop 0
	global_load_lds_dwordx4 v[196:197], off
	s_barrier
	s_waitcnt lgkmcnt(0)
	s_setprio 1
	v_mfma_f32_16x16x32_bf16 v[112:115], v[200:203], v[148:151], v[112:115]
	v_mfma_f32_16x16x32_bf16 v[112:115], v[204:207], v[152:155], v[112:115]
	v_mfma_f32_16x16x32_bf16 v[104:107], v[204:207], v[160:163], v[104:107]
	v_mfma_f32_16x16x32_bf16 v[104:107], v[200:203], v[156:159], v[104:107]
	v_mfma_f32_16x16x32_bf16 v[80:83], v[200:203], v[174:177], v[80:83]
	v_mfma_f32_16x16x32_bf16 v[80:83], v[204:207], v[178:181], v[80:83]
	v_mfma_f32_16x16x32_bf16 v[72:75], v[204:207], v[192:195], v[72:75]
	v_mfma_f32_16x16x32_bf16 v[72:75], v[200:203], v[182:185], v[72:75]
	v_mfma_f32_16x16x32_bf16 v[68:71], v[208:211], v[182:185], v[68:71]
	v_mfma_f32_16x16x32_bf16 v[68:71], v[212:215], v[192:195], v[68:71]
	v_mfma_f32_16x16x32_bf16 v[76:79], v[212:215], v[178:181], v[76:79]
	v_mfma_f32_16x16x32_bf16 v[76:79], v[208:211], v[174:177], v[76:79]
	v_mfma_f32_16x16x32_bf16 v[100:103], v[208:211], v[156:159], v[100:103]
	v_mfma_f32_16x16x32_bf16 v[100:103], v[212:215], v[160:163], v[100:103]
	v_mfma_f32_16x16x32_bf16 v[108:111], v[212:215], v[152:155], v[108:111]
	s_barrier
	v_mfma_f32_16x16x32_bf16 v[108:111], v[208:211], v[148:151], v[108:111]
	s_setprio 0
	s_mov_b32 m0, s34
	v_lshl_add_u64 v[216:217], s[24:25], 0, v[168:169]
	ds_read_b128 v[148:151], v190 offset:16384
	ds_read_b128 v[152:155], v190 offset:17408
	ds_read_b128 v[156:159], v190 offset:18432
	ds_read_b128 v[160:163], v190 offset:19456
	ds_read_b128 v[174:177], v190 offset:20480
	ds_read_b128 v[178:181], v190 offset:21504
	ds_read_b128 v[182:185], v190 offset:22528
	ds_read_b128 v[192:195], v190 offset:23552
	global_load_lds_dwordx4 v[216:217], off
	v_lshl_add_u64 v[218:219], s[24:25], 0, v[166:167]
	s_mov_b32 m0, s35
	s_nop 0
	global_load_lds_dwordx4 v[218:219], off
	s_waitcnt vmcnt(10)
	s_barrier
	s_waitcnt lgkmcnt(0)
	s_setprio 1
	v_mfma_f32_16x16x32_bf16 v[64:67], v[132:135], v[148:151], v[64:67]
	v_mfma_f32_16x16x32_bf16 v[64:67], v[136:139], v[152:155], v[64:67]
	v_mfma_f32_16x16x32_bf16 v[56:59], v[136:139], v[160:163], v[56:59]
	v_mfma_f32_16x16x32_bf16 v[56:59], v[132:135], v[156:159], v[56:59]
	v_mfma_f32_16x16x32_bf16 v[32:35], v[132:135], v[174:177], v[32:35]
	v_mfma_f32_16x16x32_bf16 v[32:35], v[136:139], v[178:181], v[32:35]
	v_mfma_f32_16x16x32_bf16 v[24:27], v[136:139], v[192:195], v[24:27]
	v_mfma_f32_16x16x32_bf16 v[24:27], v[132:135], v[182:185], v[24:27]
	v_mfma_f32_16x16x32_bf16 v[20:23], v[140:143], v[182:185], v[20:23]
	v_mfma_f32_16x16x32_bf16 v[20:23], v[144:147], v[192:195], v[20:23]
	v_mfma_f32_16x16x32_bf16 v[28:31], v[144:147], v[178:181], v[28:31]
	v_mfma_f32_16x16x32_bf16 v[28:31], v[140:143], v[174:177], v[28:31]
	v_mfma_f32_16x16x32_bf16 v[52:55], v[140:143], v[156:159], v[52:55]
	v_mfma_f32_16x16x32_bf16 v[52:55], v[144:147], v[160:163], v[52:55]
	v_mfma_f32_16x16x32_bf16 v[60:63], v[144:147], v[152:155], v[60:63]
	s_barrier
	v_mfma_f32_16x16x32_bf16 v[60:63], v[140:143], v[148:151], v[60:63]
	s_setprio 0
	s_add_u32 s50, s22, 0x80000
	s_addc_u32 s51, s23, 0
	s_add_i32 s49, s52, s31
	v_lshl_add_u64 v[132:133], s[50:51], 0, v[2:3]
	s_mov_b32 m0, s49
	s_nop 0
	global_load_lds_dwordx4 v[132:133], off
	v_lshl_add_u64 v[132:133], s[50:51], 0, v[164:165]
	s_add_i32 m0, s49, 0x2000
	s_nop 0
	global_load_lds_dwordx4 v[132:133], off
	s_add_i32 s49, 0, 0x18000
	v_add_u32_e32 v144, s49, v188
	ds_read_b128 v[132:135], v144
	ds_read_b128 v[136:139], v144 offset:1024
	ds_read_b128 v[140:143], v144 offset:2048
	ds_read_b128 v[144:147], v144 offset:3072
	s_waitcnt vmcnt(6)
	s_barrier
	s_setprio 1
	v_mfma_f32_16x16x32_bf16 v[48:51], v[200:203], v[148:151], v[48:51]
	v_mfma_f32_16x16x32_bf16 v[48:51], v[204:207], v[152:155], v[48:51]
	v_mfma_f32_16x16x32_bf16 v[40:43], v[204:207], v[160:163], v[40:43]
	v_mfma_f32_16x16x32_bf16 v[40:43], v[200:203], v[156:159], v[40:43]
	v_mfma_f32_16x16x32_bf16 v[16:19], v[200:203], v[174:177], v[16:19]
	v_mfma_f32_16x16x32_bf16 v[16:19], v[204:207], v[178:181], v[16:19]
	v_mfma_f32_16x16x32_bf16 v[8:11], v[204:207], v[192:195], v[8:11]
	v_mfma_f32_16x16x32_bf16 v[8:11], v[200:203], v[182:185], v[8:11]
	v_mfma_f32_16x16x32_bf16 v[4:7], v[208:211], v[182:185], v[4:7]
	v_mfma_f32_16x16x32_bf16 v[4:7], v[212:215], v[192:195], v[4:7]
	v_mfma_f32_16x16x32_bf16 v[12:15], v[212:215], v[178:181], v[12:15]
	v_mfma_f32_16x16x32_bf16 v[12:15], v[208:211], v[174:177], v[12:15]
	v_mfma_f32_16x16x32_bf16 v[36:39], v[208:211], v[156:159], v[36:39]
	v_mfma_f32_16x16x32_bf16 v[36:39], v[212:215], v[160:163], v[36:39]
	v_mfma_f32_16x16x32_bf16 v[44:47], v[212:215], v[152:155], v[44:47]
	s_barrier
	v_mfma_f32_16x16x32_bf16 v[44:47], v[208:211], v[148:151], v[44:47]
	s_setprio 0
	s_add_u32 s24, s24, 0x80000
	s_addc_u32 s25, s25, 0
	s_mov_b32 m0, s36
	v_lshl_add_u64 v[200:201], s[24:25], 0, v[168:169]
	ds_read_b128 v[148:151], v190 offset:32768
	ds_read_b128 v[152:155], v190 offset:33792
	ds_read_b128 v[156:159], v190 offset:34816
	ds_read_b128 v[160:163], v190 offset:35840
	ds_read_b128 v[174:177], v190 offset:36864
	ds_read_b128 v[178:181], v190 offset:37888
	ds_read_b128 v[182:185], v190 offset:38912
	ds_read_b128 v[192:195], v190 offset:39936
	global_load_lds_dwordx4 v[200:201], off
	v_lshl_add_u64 v[200:201], s[24:25], 0, v[166:167]
	s_mov_b32 m0, s37
	s_nop 0
	global_load_lds_dwordx4 v[200:201], off
	s_waitcnt lgkmcnt(8)
	s_barrier
	s_waitcnt lgkmcnt(0)
	s_setprio 1
	v_mfma_f32_16x16x32_bf16 v[128:131], v[132:135], v[148:151], v[128:131]
	v_mfma_f32_16x16x32_bf16 v[128:131], v[136:139], v[152:155], v[128:131]
	v_mfma_f32_16x16x32_bf16 v[120:123], v[136:139], v[160:163], v[120:123]
	v_mfma_f32_16x16x32_bf16 v[120:123], v[132:135], v[156:159], v[120:123]
	v_mfma_f32_16x16x32_bf16 v[96:99], v[132:135], v[174:177], v[96:99]
	v_mfma_f32_16x16x32_bf16 v[96:99], v[136:139], v[178:181], v[96:99]
	v_mfma_f32_16x16x32_bf16 v[88:91], v[136:139], v[192:195], v[88:91]
	v_mfma_f32_16x16x32_bf16 v[88:91], v[132:135], v[182:185], v[88:91]
	v_mfma_f32_16x16x32_bf16 v[84:87], v[140:143], v[182:185], v[84:87]
	v_mfma_f32_16x16x32_bf16 v[84:87], v[144:147], v[192:195], v[84:87]
	v_mfma_f32_16x16x32_bf16 v[92:95], v[144:147], v[178:181], v[92:95]
	v_mfma_f32_16x16x32_bf16 v[92:95], v[140:143], v[174:177], v[92:95]
	v_mfma_f32_16x16x32_bf16 v[116:119], v[140:143], v[156:159], v[116:119]
	v_mfma_f32_16x16x32_bf16 v[116:119], v[144:147], v[160:163], v[116:119]
	v_mfma_f32_16x16x32_bf16 v[124:127], v[144:147], v[152:155], v[124:127]
	s_barrier
	v_mfma_f32_16x16x32_bf16 v[124:127], v[140:143], v[148:151], v[124:127]
	s_setprio 0
	s_add_i32 s24, 0, 0x1c000
	s_add_i32 s25, s49, s31
	v_add_u32_e32 v191, s24, v188
	v_lshl_add_u64 v[186:187], v[186:187], 0, s[2:3]
	s_mov_b32 m0, s25
	ds_read_b128 v[200:203], v191
	ds_read_b128 v[204:207], v191 offset:1024
	ds_read_b128 v[208:211], v191 offset:2048
	ds_read_b128 v[212:215], v191 offset:3072
	global_load_lds_dwordx4 v[186:187], off
	v_lshl_add_u64 v[186:187], v[196:197], 0, s[2:3]
	s_add_i32 m0, s25, 0x2000
	s_nop 0
	global_load_lds_dwordx4 v[186:187], off
	s_barrier
	s_waitcnt lgkmcnt(0)
	s_setprio 1
	v_mfma_f32_16x16x32_bf16 v[112:115], v[200:203], v[148:151], v[112:115]
	v_mfma_f32_16x16x32_bf16 v[112:115], v[204:207], v[152:155], v[112:115]
	v_mfma_f32_16x16x32_bf16 v[104:107], v[204:207], v[160:163], v[104:107]
	v_mfma_f32_16x16x32_bf16 v[104:107], v[200:203], v[156:159], v[104:107]
	v_mfma_f32_16x16x32_bf16 v[80:83], v[200:203], v[174:177], v[80:83]
	v_mfma_f32_16x16x32_bf16 v[80:83], v[204:207], v[178:181], v[80:83]
	v_mfma_f32_16x16x32_bf16 v[72:75], v[204:207], v[192:195], v[72:75]
	v_mfma_f32_16x16x32_bf16 v[72:75], v[200:203], v[182:185], v[72:75]
	v_mfma_f32_16x16x32_bf16 v[68:71], v[208:211], v[182:185], v[68:71]
	v_mfma_f32_16x16x32_bf16 v[68:71], v[212:215], v[192:195], v[68:71]
	v_mfma_f32_16x16x32_bf16 v[76:79], v[212:215], v[178:181], v[76:79]
	v_mfma_f32_16x16x32_bf16 v[76:79], v[208:211], v[174:177], v[76:79]
	v_mfma_f32_16x16x32_bf16 v[100:103], v[208:211], v[156:159], v[100:103]
	v_mfma_f32_16x16x32_bf16 v[100:103], v[212:215], v[160:163], v[100:103]
	v_mfma_f32_16x16x32_bf16 v[108:111], v[212:215], v[152:155], v[108:111]
	s_barrier
	v_mfma_f32_16x16x32_bf16 v[108:111], v[208:211], v[148:151], v[108:111]
	s_setprio 0
	s_mov_b32 m0, s41
	v_lshl_add_u64 v[186:187], v[216:217], 0, s[2:3]
	ds_read_b128 v[148:151], v190 offset:49152
	ds_read_b128 v[152:155], v190 offset:50176
	ds_read_b128 v[156:159], v190 offset:51200
	ds_read_b128 v[160:163], v190 offset:52224
	ds_read_b128 v[174:177], v190 offset:53248
	ds_read_b128 v[178:181], v190 offset:54272
	ds_read_b128 v[182:185], v190 offset:55296
	ds_read_b128 v[192:195], v190 offset:56320
	global_load_lds_dwordx4 v[186:187], off
	v_lshl_add_u64 v[186:187], v[218:219], 0, s[2:3]
	s_mov_b32 m0, s42
	s_nop 0
	global_load_lds_dwordx4 v[186:187], off
	s_barrier
	s_waitcnt lgkmcnt(0)
	s_setprio 1
	v_mfma_f32_16x16x32_bf16 v[64:67], v[132:135], v[148:151], v[64:67]
	v_mfma_f32_16x16x32_bf16 v[64:67], v[136:139], v[152:155], v[64:67]
	v_mfma_f32_16x16x32_bf16 v[56:59], v[136:139], v[160:163], v[56:59]
	v_mfma_f32_16x16x32_bf16 v[56:59], v[132:135], v[156:159], v[56:59]
	v_mfma_f32_16x16x32_bf16 v[32:35], v[132:135], v[174:177], v[32:35]
	v_mfma_f32_16x16x32_bf16 v[32:35], v[136:139], v[178:181], v[32:35]
	v_mfma_f32_16x16x32_bf16 v[24:27], v[136:139], v[192:195], v[24:27]
	v_mfma_f32_16x16x32_bf16 v[24:27], v[132:135], v[182:185], v[24:27]
	v_mfma_f32_16x16x32_bf16 v[20:23], v[140:143], v[182:185], v[20:23]
	v_mfma_f32_16x16x32_bf16 v[20:23], v[144:147], v[192:195], v[20:23]
	v_mfma_f32_16x16x32_bf16 v[28:31], v[144:147], v[178:181], v[28:31]
	v_mfma_f32_16x16x32_bf16 v[28:31], v[140:143], v[174:177], v[28:31]
	v_mfma_f32_16x16x32_bf16 v[52:55], v[140:143], v[156:159], v[52:55]
	v_mfma_f32_16x16x32_bf16 v[52:55], v[144:147], v[160:163], v[52:55]
	v_mfma_f32_16x16x32_bf16 v[60:63], v[144:147], v[152:155], v[60:63]
	s_barrier
	v_mfma_f32_16x16x32_bf16 v[60:63], v[140:143], v[148:151], v[60:63]
	s_setprio 0
	s_add_u32 s22, s22, 0x80080
	s_addc_u32 s23, s23, 0
	s_add_i32 s24, s24, s31
	v_lshl_add_u64 v[132:133], s[22:23], 0, v[2:3]
	s_mov_b32 m0, s24
	s_nop 0
	global_load_lds_dwordx4 v[132:133], off
	v_lshl_add_u64 v[132:133], s[22:23], 0, v[164:165]
	s_add_i32 m0, s24, 0x2000
	s_nop 0
	global_load_lds_dwordx4 v[132:133], off
	s_waitcnt vmcnt(6)
	s_barrier
	s_setprio 1
	v_mfma_f32_16x16x32_bf16 v[48:51], v[200:203], v[148:151], v[48:51]
	v_mfma_f32_16x16x32_bf16 v[48:51], v[204:207], v[152:155], v[48:51]
	v_mfma_f32_16x16x32_bf16 v[40:43], v[204:207], v[160:163], v[40:43]
	v_mfma_f32_16x16x32_bf16 v[40:43], v[200:203], v[156:159], v[40:43]
	v_mfma_f32_16x16x32_bf16 v[16:19], v[200:203], v[174:177], v[16:19]
	v_mfma_f32_16x16x32_bf16 v[16:19], v[204:207], v[178:181], v[16:19]
	v_mfma_f32_16x16x32_bf16 v[8:11], v[204:207], v[192:195], v[8:11]
	v_mfma_f32_16x16x32_bf16 v[8:11], v[200:203], v[182:185], v[8:11]
	v_mfma_f32_16x16x32_bf16 v[4:7], v[208:211], v[182:185], v[4:7]
	v_mfma_f32_16x16x32_bf16 v[4:7], v[212:215], v[192:195], v[4:7]
	v_mfma_f32_16x16x32_bf16 v[12:15], v[212:215], v[178:181], v[12:15]
	v_mfma_f32_16x16x32_bf16 v[12:15], v[208:211], v[174:177], v[12:15]
	v_mfma_f32_16x16x32_bf16 v[36:39], v[208:211], v[156:159], v[36:39]
	v_mfma_f32_16x16x32_bf16 v[36:39], v[212:215], v[160:163], v[36:39]
	v_mfma_f32_16x16x32_bf16 v[44:47], v[212:215], v[152:155], v[44:47]
	s_barrier
	v_mfma_f32_16x16x32_bf16 v[44:47], v[208:211], v[148:151], v[44:47]
	s_setprio 0
	s_add_i32 s48, s48, 2
	s_add_u32 s20, s20, 0x100
	s_addc_u32 s21, s21, 0
	s_add_u32 s46, s46, 0x100
	s_addc_u32 s47, s47, 0
	s_cmp_gt_u32 s48, 29
	s_cbranch_scc0 .LBB0_878
	s_cmp_lt_i32 s43, 32
	s_mov_b64 s[20:21], 0
	s_cbranch_scc1 .LBB0_881
	s_sub_i32 s13, s43, 32
	s_lshr_b32 s13, s13, 4
	s_add_i32 s13, s13, 1
	s_mul_hi_u32 s21, s13, 0x3000
	s_mul_i32 s20, s13, 0x3000

.LBB0_1002:
	s_add_u32 s28, s26, 0x100
	s_addc_u32 s29, s27, 0
	s_add_i32 s58, 0, 0x10000
	v_add_u32_e32 v56, s58, v1
	ds_read_b128 v[44:47], v56
	ds_read_b128 v[48:51], v56 offset:1024
	ds_read_b128 v[52:55], v56 offset:2048
	ds_read_b128 v[56:59], v56 offset:3072
	s_cmp_eq_u32 s57, 28
	s_cselect_b32 s35, s21, s29
	s_cselect_b32 s34, s53, s28
	s_cselect_b32 s31, s19, s56
	s_cselect_b32 s30, s54, s55
	v_lshl_add_u64 v[190:191], s[26:27], 0, v[178:179]
	s_add_i32 m0, s42, 0xc000
	ds_read_b128 v[68:71], v200
	ds_read_b128 v[72:75], v200 offset:1024
	ds_read_b128 v[76:79], v200 offset:2048
	ds_read_b128 v[80:83], v200 offset:3072
	ds_read_b128 v[164:167], v200 offset:4096
	ds_read_b128 v[168:171], v200 offset:5120
	ds_read_b128 v[182:185], v200 offset:6144
	ds_read_b128 v[186:189], v200 offset:7168
	global_load_lds_dwordx4 v[190:191], off
	v_lshl_add_u64 v[190:191], s[26:27], 0, v[180:181]
	s_add_i32 m0, s42, 0xe000
	s_nop 0
	global_load_lds_dwordx4 v[190:191], off
	s_waitcnt lgkmcnt(8)
	s_barrier
	s_waitcnt lgkmcnt(0)
	s_setprio 1
	v_mfma_f32_16x16x32_bf16 v[160:163], v[44:47], v[68:71], v[160:163]
	v_mfma_f32_16x16x32_bf16 v[160:163], v[48:51], v[72:75], v[160:163]
	v_mfma_f32_16x16x32_bf16 v[148:151], v[48:51], v[80:83], v[148:151]
	v_mfma_f32_16x16x32_bf16 v[148:151], v[44:47], v[76:79], v[148:151]
	v_mfma_f32_16x16x32_bf16 v[132:135], v[44:47], v[164:167], v[132:135]
	v_mfma_f32_16x16x32_bf16 v[132:135], v[48:51], v[168:171], v[132:135]
	v_mfma_f32_16x16x32_bf16 v[116:119], v[48:51], v[186:189], v[116:119]
	v_mfma_f32_16x16x32_bf16 v[116:119], v[44:47], v[182:185], v[116:119]
	v_mfma_f32_16x16x32_bf16 v[108:111], v[52:55], v[182:185], v[108:111]
	v_mfma_f32_16x16x32_bf16 v[108:111], v[56:59], v[186:189], v[108:111]
	v_mfma_f32_16x16x32_bf16 v[124:127], v[56:59], v[168:171], v[124:127]
	v_mfma_f32_16x16x32_bf16 v[124:127], v[52:55], v[164:167], v[124:127]
	v_mfma_f32_16x16x32_bf16 v[140:143], v[52:55], v[76:79], v[140:143]
	v_mfma_f32_16x16x32_bf16 v[140:143], v[56:59], v[80:83], v[140:143]
	v_mfma_f32_16x16x32_bf16 v[156:159], v[56:59], v[72:75], v[156:159]
	s_barrier
	v_mfma_f32_16x16x32_bf16 v[156:159], v[52:55], v[68:71], v[156:159]
	s_setprio 0
	s_add_i32 s59, 0, 0x14000
	v_add_u32_e32 v194, s59, v1
	s_add_i32 s26, s58, s41
	ds_read_b128 v[190:193], v194
	ds_read_b128 v[202:205], v194 offset:1024
	ds_read_b128 v[206:209], v194 offset:2048
	ds_read_b128 v[210:213], v194 offset:3072
	v_lshl_add_u64 v[194:195], s[30:31], 0, v[2:3]
	s_mov_b32 m0, s26
	v_lshl_add_u64 v[222:223], s[30:31], 0, v[172:173]
	global_load_lds_dwordx4 v[194:195], off
	s_add_i32 m0, s26, 0x2000
	s_nop 0
	global_load_lds_dwordx4 v[222:223], off
	s_barrier
	s_waitcnt lgkmcnt(0)
	s_setprio 1
	v_mfma_f32_16x16x32_bf16 v[152:155], v[190:193], v[68:71], v[152:155]
	v_mfma_f32_16x16x32_bf16 v[152:155], v[202:205], v[72:75], v[152:155]
	v_mfma_f32_16x16x32_bf16 v[68:71], v[206:209], v[68:71], v[144:147]
	v_mfma_f32_16x16x32_bf16 v[68:71], v[210:213], v[72:75], v[68:71]
	v_mfma_f32_16x16x32_bf16 v[72:75], v[190:193], v[76:79], v[136:139]
	v_mfma_f32_16x16x32_bf16 v[72:75], v[202:205], v[80:83], v[72:75]
	v_mfma_f32_16x16x32_bf16 v[76:79], v[206:209], v[76:79], v[128:131]
	v_mfma_f32_16x16x32_bf16 v[76:79], v[210:213], v[80:83], v[76:79]
	v_mfma_f32_16x16x32_bf16 v[112:115], v[206:209], v[164:167], v[112:115]
	v_mfma_f32_16x16x32_bf16 v[112:115], v[210:213], v[168:171], v[112:115]
	v_mfma_f32_16x16x32_bf16 v[104:107], v[190:193], v[182:185], v[104:107]
	v_mfma_f32_16x16x32_bf16 v[104:107], v[202:205], v[186:189], v[104:107]
	v_mfma_f32_16x16x32_bf16 v[96:99], v[206:209], v[182:185], v[96:99]
	v_mfma_f32_16x16x32_bf16 v[96:99], v[210:213], v[186:189], v[96:99]
	v_mfma_f32_16x16x32_bf16 v[80:83], v[190:193], v[164:167], v[120:123]
	s_barrier
	v_mfma_f32_16x16x32_bf16 v[80:83], v[202:205], v[168:171], v[80:83]
	s_setprio 0
	s_mov_b32 m0, s42
	v_lshl_add_u64 v[224:225], s[34:35], 0, v[176:177]
	ds_read_b128 v[120:123], v200 offset:16384
	ds_read_b128 v[128:131], v200 offset:17408
	ds_read_b128 v[136:139], v200 offset:18432
	ds_read_b128 v[144:147], v200 offset:19456
	ds_read_b128 v[164:167], v200 offset:20480
	ds_read_b128 v[168:171], v200 offset:21504
	ds_read_b128 v[182:185], v200 offset:22528
	ds_read_b128 v[186:189], v200 offset:23552
	global_load_lds_dwordx4 v[224:225], off
	v_lshl_add_u64 v[226:227], s[34:35], 0, v[174:175]
	s_mov_b32 m0, s43
	s_nop 0
	global_load_lds_dwordx4 v[226:227], off
	s_waitcnt vmcnt(10)
	s_barrier
	s_waitcnt lgkmcnt(0)
	s_setprio 1
	v_mfma_f32_16x16x32_bf16 v[100:103], v[44:47], v[120:123], v[100:103]
	v_mfma_f32_16x16x32_bf16 v[100:103], v[48:51], v[128:131], v[100:103]
	v_mfma_f32_16x16x32_bf16 v[84:87], v[48:51], v[144:147], v[84:87]
	v_mfma_f32_16x16x32_bf16 v[84:87], v[44:47], v[136:139], v[84:87]
	v_mfma_f32_16x16x32_bf16 v[36:39], v[44:47], v[164:167], v[36:39]
	v_mfma_f32_16x16x32_bf16 v[36:39], v[48:51], v[168:171], v[36:39]
	v_mfma_f32_16x16x32_bf16 v[16:19], v[48:51], v[186:189], v[16:19]
	v_mfma_f32_16x16x32_bf16 v[16:19], v[44:47], v[182:185], v[16:19]
	v_mfma_f32_16x16x32_bf16 v[12:15], v[52:55], v[182:185], v[12:15]
	v_mfma_f32_16x16x32_bf16 v[12:15], v[56:59], v[186:189], v[12:15]
	v_mfma_f32_16x16x32_bf16 v[28:31], v[56:59], v[168:171], v[28:31]
	v_mfma_f32_16x16x32_bf16 v[28:31], v[52:55], v[164:167], v[28:31]
	v_mfma_f32_16x16x32_bf16 v[60:63], v[52:55], v[136:139], v[60:63]
	v_mfma_f32_16x16x32_bf16 v[60:63], v[56:59], v[144:147], v[60:63]
	v_mfma_f32_16x16x32_bf16 v[92:95], v[56:59], v[128:131], v[92:95]
	s_barrier
	v_mfma_f32_16x16x32_bf16 v[92:95], v[52:55], v[120:123], v[92:95]
	s_setprio 0
	s_add_u32 s26, s30, 0x80000
	s_addc_u32 s27, s31, 0
	s_add_i32 s58, s59, s41
	v_lshl_add_u64 v[44:45], s[26:27], 0, v[2:3]
	s_mov_b32 m0, s58
	s_nop 0
	global_load_lds_dwordx4 v[44:45], off
	v_lshl_add_u64 v[44:45], s[26:27], 0, v[172:173]
	s_add_i32 m0, s58, 0x2000
	s_nop 0
	global_load_lds_dwordx4 v[44:45], off
	s_add_i32 s58, 0, 0x18000
	v_add_u32_e32 v44, s58, v1
	ds_read_b128 v[52:55], v44
	ds_read_b128 v[56:59], v44 offset:1024
	s_waitcnt vmcnt(6)
	s_barrier
	s_setprio 1
	v_mfma_f32_16x16x32_bf16 v[40:43], v[190:193], v[136:139], v[40:43]
	v_mfma_f32_16x16x32_bf16 v[40:43], v[202:205], v[144:147], v[40:43]
	v_mfma_f32_16x16x32_bf16 v[24:27], v[202:205], v[168:171], v[24:27]
	v_mfma_f32_16x16x32_bf16 v[24:27], v[190:193], v[164:167], v[24:27]
	v_mfma_f32_16x16x32_bf16 v[8:11], v[190:193], v[182:185], v[8:11]
	v_mfma_f32_16x16x32_bf16 v[8:11], v[202:205], v[186:189], v[8:11]
	v_mfma_f32_16x16x32_bf16 v[44:47], v[202:205], v[128:131], v[88:91]
	v_mfma_f32_16x16x32_bf16 v[44:47], v[190:193], v[120:123], v[44:47]
	v_mfma_f32_16x16x32_bf16 v[48:51], v[206:209], v[120:123], v[64:67]
	v_mfma_f32_16x16x32_bf16 v[48:51], v[210:213], v[128:131], v[48:51]
	v_mfma_f32_16x16x32_bf16 v[4:7], v[210:213], v[186:189], v[4:7]
	v_mfma_f32_16x16x32_bf16 v[4:7], v[206:209], v[182:185], v[4:7]
	v_mfma_f32_16x16x32_bf16 v[20:23], v[206:209], v[164:167], v[20:23]
	v_mfma_f32_16x16x32_bf16 v[20:23], v[210:213], v[168:171], v[20:23]
	v_mfma_f32_16x16x32_bf16 v[32:35], v[210:213], v[144:147], v[32:35]
	s_barrier
	v_mfma_f32_16x16x32_bf16 v[32:35], v[206:209], v[136:139], v[32:35]
	s_setprio 0
	v_add_u32_e32 v88, s58, v1
	ds_read_b128 v[64:67], v88 offset:2048
	ds_read_b128 v[88:91], v88 offset:3072
	s_add_u32 s26, s34, 0x4000
	s_addc_u32 s27, s35, 0
	s_mov_b32 m0, s44
	v_lshl_add_u64 v[136:137], s[26:27], 0, v[176:177]
	ds_read_b128 v[120:123], v200 offset:32768
	ds_read_b128 v[128:131], v200 offset:33792
	ds_read_b128 v[164:167], v200 offset:34816
	ds_read_b128 v[168:171], v200 offset:35840
	ds_read_b128 v[182:185], v200 offset:36864
	ds_read_b128 v[186:189], v200 offset:37888
	ds_read_b128 v[190:193], v200 offset:38912
	ds_read_b128 v[202:205], v200 offset:39936
	global_load_lds_dwordx4 v[136:137], off
	v_lshl_add_u64 v[136:137], s[26:27], 0, v[174:175]
	s_mov_b32 m0, s45
	s_nop 0
	global_load_lds_dwordx4 v[136:137], off
	s_waitcnt lgkmcnt(8)
	s_barrier
	s_waitcnt lgkmcnt(0)
	s_setprio 1
	v_mfma_f32_16x16x32_bf16 v[136:139], v[52:55], v[120:123], v[160:163]
	v_mfma_f32_16x16x32_bf16 v[160:163], v[56:59], v[128:131], v[136:139]
	v_mfma_f32_16x16x32_bf16 v[136:139], v[64:67], v[120:123], v[156:159]
	v_mfma_f32_16x16x32_bf16 v[156:159], v[88:91], v[128:131], v[136:139]
	v_mfma_f32_16x16x32_bf16 v[136:139], v[52:55], v[164:167], v[148:151]
	v_mfma_f32_16x16x32_bf16 v[148:151], v[56:59], v[168:171], v[136:139]
	v_mfma_f32_16x16x32_bf16 v[136:139], v[64:67], v[164:167], v[140:143]
	v_mfma_f32_16x16x32_bf16 v[140:143], v[88:91], v[168:171], v[136:139]
	v_mfma_f32_16x16x32_bf16 v[132:135], v[52:55], v[182:185], v[132:135]
	v_mfma_f32_16x16x32_bf16 v[132:135], v[56:59], v[186:189], v[132:135]
	v_mfma_f32_16x16x32_bf16 v[124:127], v[64:67], v[182:185], v[124:127]
	v_mfma_f32_16x16x32_bf16 v[124:127], v[88:91], v[186:189], v[124:127]
	v_mfma_f32_16x16x32_bf16 v[116:119], v[52:55], v[190:193], v[116:119]
	v_mfma_f32_16x16x32_bf16 v[116:119], v[56:59], v[202:205], v[116:119]
	v_mfma_f32_16x16x32_bf16 v[108:111], v[64:67], v[190:193], v[108:111]
	s_barrier
	v_mfma_f32_16x16x32_bf16 v[108:111], v[88:91], v[202:205], v[108:111]
	s_setprio 0
	s_add_i32 s34, 0, 0x1c000
	v_add_u32_e32 v136, s34, v1
	s_add_i32 s26, s58, s41
	ds_read_b128 v[206:209], v136
	ds_read_b128 v[210:213], v136 offset:1024
	ds_read_b128 v[214:217], v136 offset:2048
	ds_read_b128 v[218:221], v136 offset:3072
	v_lshl_add_u64 v[136:137], v[194:195], 0, s[2:3]
	s_mov_b32 m0, s26
	s_nop 0
	global_load_lds_dwordx4 v[136:137], off
	v_lshl_add_u64 v[136:137], v[222:223], 0, s[2:3]
	s_add_i32 m0, s26, 0x2000
	s_nop 0
	global_load_lds_dwordx4 v[136:137], off
	s_barrier
	s_waitcnt lgkmcnt(0)
	s_setprio 1
	v_mfma_f32_16x16x32_bf16 v[68:71], v[214:217], v[120:123], v[68:71]
	v_mfma_f32_16x16x32_bf16 v[144:147], v[218:221], v[128:131], v[68:71]
	v_mfma_f32_16x16x32_bf16 v[136:139], v[206:209], v[120:123], v[152:155]
	v_mfma_f32_16x16x32_bf16 v[152:155], v[210:213], v[128:131], v[136:139]
	v_mfma_f32_16x16x32_bf16 v[68:71], v[206:209], v[164:167], v[72:75]
	v_mfma_f32_16x16x32_bf16 v[136:139], v[210:213], v[168:171], v[68:71]
	v_mfma_f32_16x16x32_bf16 v[68:71], v[214:217], v[164:167], v[76:79]
	v_mfma_f32_16x16x32_bf16 v[128:131], v[218:221], v[168:171], v[68:71]
	v_mfma_f32_16x16x32_bf16 v[68:71], v[206:209], v[182:185], v[80:83]
	v_mfma_f32_16x16x32_bf16 v[120:123], v[210:213], v[186:189], v[68:71]
	v_mfma_f32_16x16x32_bf16 v[68:71], v[214:217], v[182:185], v[112:115]
	v_mfma_f32_16x16x32_bf16 v[112:115], v[218:221], v[186:189], v[68:71]
	v_mfma_f32_16x16x32_bf16 v[68:71], v[206:209], v[190:193], v[104:107]
	v_mfma_f32_16x16x32_bf16 v[104:107], v[210:213], v[202:205], v[68:71]
	v_mfma_f32_16x16x32_bf16 v[68:71], v[214:217], v[190:193], v[96:99]
	s_barrier
	v_mfma_f32_16x16x32_bf16 v[96:99], v[218:221], v[202:205], v[68:71]
	s_setprio 0
	s_mov_b32 m0, s48
	v_lshl_add_u64 v[190:191], v[224:225], 0, s[2:3]
	s_nop 2
	ds_read_b128 v[68:71], v200 offset:49152
	ds_read_b128 v[72:75], v200 offset:50176
	ds_read_b128 v[76:79], v200 offset:51200
	ds_read_b128 v[80:83], v200 offset:52224
	ds_read_b128 v[164:167], v200 offset:53248
	ds_read_b128 v[168:171], v200 offset:54272
	ds_read_b128 v[182:185], v200 offset:55296
	ds_read_b128 v[186:189], v200 offset:56320
	global_load_lds_dwordx4 v[190:191], off
	v_lshl_add_u64 v[190:191], v[226:227], 0, s[2:3]
	s_mov_b32 m0, s49
	s_nop 0
	global_load_lds_dwordx4 v[190:191], off
	s_barrier
	s_waitcnt lgkmcnt(0)
	s_setprio 1
	v_mfma_f32_16x16x32_bf16 v[100:103], v[52:55], v[68:71], v[100:103]
	v_mfma_f32_16x16x32_bf16 v[100:103], v[56:59], v[72:75], v[100:103]
	v_mfma_f32_16x16x32_bf16 v[84:87], v[56:59], v[80:83], v[84:87]
	v_mfma_f32_16x16x32_bf16 v[84:87], v[52:55], v[76:79], v[84:87]
	v_mfma_f32_16x16x32_bf16 v[36:39], v[52:55], v[164:167], v[36:39]
	v_mfma_f32_16x16x32_bf16 v[36:39], v[56:59], v[168:171], v[36:39]
	v_mfma_f32_16x16x32_bf16 v[16:19], v[56:59], v[186:189], v[16:19]
	v_mfma_f32_16x16x32_bf16 v[16:19], v[52:55], v[182:185], v[16:19]
	v_mfma_f32_16x16x32_bf16 v[12:15], v[64:67], v[182:185], v[12:15]
	v_mfma_f32_16x16x32_bf16 v[12:15], v[88:91], v[186:189], v[12:15]
	v_mfma_f32_16x16x32_bf16 v[28:31], v[88:91], v[168:171], v[28:31]
	v_mfma_f32_16x16x32_bf16 v[28:31], v[64:67], v[164:167], v[28:31]
	v_mfma_f32_16x16x32_bf16 v[60:63], v[64:67], v[76:79], v[60:63]
	v_mfma_f32_16x16x32_bf16 v[60:63], v[88:91], v[80:83], v[60:63]
	v_mfma_f32_16x16x32_bf16 v[92:95], v[88:91], v[72:75], v[92:95]
	s_barrier
	v_mfma_f32_16x16x32_bf16 v[92:95], v[64:67], v[68:71], v[92:95]
	s_setprio 0
	s_add_u32 s26, s30, 0x80080
	s_addc_u32 s27, s31, 0
	s_add_i32 s30, s34, s41
	s_mov_b32 m0, s30
	s_nop 0
	global_load_lds_dwordx4 v2, s[26:27]
	s_add_i32 m0, s30, 0x2000
	s_nop 0
	global_load_lds_dwordx4 v172, s[26:27]
	s_waitcnt vmcnt(6)
	s_barrier
	s_setprio 1
	v_mfma_f32_16x16x32_bf16 v[44:47], v[206:209], v[68:71], v[44:47]
	v_mfma_f32_16x16x32_bf16 v[88:91], v[210:213], v[72:75], v[44:47]
	v_mfma_f32_16x16x32_bf16 v[44:47], v[214:217], v[68:71], v[48:51]
	v_mfma_f32_16x16x32_bf16 v[64:67], v[218:221], v[72:75], v[44:47]
	v_mfma_f32_16x16x32_bf16 v[40:43], v[206:209], v[76:79], v[40:43]
	v_mfma_f32_16x16x32_bf16 v[40:43], v[210:213], v[80:83], v[40:43]
	v_mfma_f32_16x16x32_bf16 v[32:35], v[214:217], v[76:79], v[32:35]
	v_mfma_f32_16x16x32_bf16 v[32:35], v[218:221], v[80:83], v[32:35]
	v_mfma_f32_16x16x32_bf16 v[24:27], v[206:209], v[164:167], v[24:27]
	v_mfma_f32_16x16x32_bf16 v[24:27], v[210:213], v[168:171], v[24:27]
	v_mfma_f32_16x16x32_bf16 v[20:23], v[214:217], v[164:167], v[20:23]
	v_mfma_f32_16x16x32_bf16 v[20:23], v[218:221], v[168:171], v[20:23]
	v_mfma_f32_16x16x32_bf16 v[8:11], v[206:209], v[182:185], v[8:11]
	v_mfma_f32_16x16x32_bf16 v[8:11], v[210:213], v[186:189], v[8:11]
	v_mfma_f32_16x16x32_bf16 v[4:7], v[214:217], v[182:185], v[4:7]
	s_barrier
	v_mfma_f32_16x16x32_bf16 v[4:7], v[218:221], v[186:189], v[4:7]
	s_setprio 0
	s_add_i32 s57, s57, 2
	s_add_u32 s55, s55, 0x100
	s_addc_u32 s56, s56, 0
	s_cmp_gt_u32 s57, 29
	s_mov_b64 s[26:27], s[28:29]
	s_cbranch_scc0 .LBB0_1002
	v_lshl_or_b32 v182, s52, 7, v197
	v_ashrrev_i32_e32 v183, 31, v182
	v_lshlrev_b64 v[56:57], 2, v[182:183]
	v_lshl_add_u64 v[48:49], s[10:11], 0, v[56:57]
	global_load_dwordx4 v[44:47], v[48:49], off offset:16
	global_load_dwordx4 v[68:71], v[48:49], off
	v_lshl_add_u64 v[52:53], s[14:15], 0, v[56:57]
	global_load_dwordx4 v[48:51], v[52:53], off offset:16
	global_load_dwordx4 v[72:75], v[52:53], off
	v_lshl_add_u64 v[58:59], s[16:17], 0, v[56:57]
	global_load_dwordx4 v[52:55], v[58:59], off offset:16
	global_load_dwordx4 v[76:79], v[58:59], off
	v_lshl_add_u64 v[80:81], s[12:13], 0, v[56:57]
	global_load_dwordx4 v[56:59], v[80:81], off offset:16
	s_nop 0
	global_load_dwordx4 v[80:83], v[80:81], off
	v_mov_b32_dpp v164, v8 row_shr:1 row_mask:0xf bank_mask:0xf bound_ctrl:1
	v_mov_b32_dpp v165, v9 row_shr:1 row_mask:0xf bank_mask:0xf bound_ctrl:1
	v_mov_b32_dpp v166, v10 row_shr:1 row_mask:0xf bank_mask:0xf bound_ctrl:1
	v_mov_b32_dpp v167, v11 row_shr:1 row_mask:0xf bank_mask:0xf bound_ctrl:1
	v_mov_b32_dpp v168, v4 row_shr:1 row_mask:0xf bank_mask:0xf bound_ctrl:1
	v_mov_b32_dpp v169, v5 row_shr:1 row_mask:0xf bank_mask:0xf bound_ctrl:1
	v_mov_b32_dpp v170, v6 row_shr:1 row_mask:0xf bank_mask:0xf bound_ctrl:1
	v_mov_b32_dpp v171, v7 row_shr:1 row_mask:0xf bank_mask:0xf bound_ctrl:1
	v_lshl_add_u32 v201, s33, 8, v196
	s_movk_i32 s21, 0x2c00
	s_lshl_b32 s19, s33, 2
	v_mov_b32_dpp v190, v152 row_shl:1 row_mask:0xf bank_mask:0xf bound_ctrl:1
	v_mov_b32_dpp v191, v153 row_shl:1 row_mask:0xf bank_mask:0xf bound_ctrl:1
	v_mov_b32_dpp v188, v154 row_shl:1 row_mask:0xf bank_mask:0xf bound_ctrl:1
	v_mov_b32_dpp v189, v155 row_shl:1 row_mask:0xf bank_mask:0xf bound_ctrl:1
	v_mov_b32_dpp v186, v144 row_shl:1 row_mask:0xf bank_mask:0xf bound_ctrl:1
	v_mov_b32_dpp v187, v145 row_shl:1 row_mask:0xf bank_mask:0xf bound_ctrl:1
	v_mov_b32_dpp v184, v146 row_shl:1 row_mask:0xf bank_mask:0xf bound_ctrl:1
	v_mov_b32_dpp v185, v147 row_shl:1 row_mask:0xf bank_mask:0xf bound_ctrl:1
	s_add_i32 s19, s19, s50
	s_waitcnt vmcnt(0)
	v_pk_mul_f32 v[168:169], v[44:45], v[168:169]
	v_pk_mul_f32 v[164:165], v[68:69], v[164:165]
	v_pk_mul_f32 v[166:167], v[70:71], v[166:167]
	v_pk_fma_f32 v[164:165], v[152:153], v[72:73], v[164:165]
	v_pk_fma_f32 v[166:167], v[154:155], v[74:75], v[166:167]
	v_pk_fma_f32 v[164:165], v[136:137], v[76:77], v[164:165]
	v_pk_fma_f32 v[166:167], v[138:139], v[78:79], v[166:167]
	v_pk_add_f32 v[164:165], v[80:81], v[164:165]
	v_pk_add_f32 v[166:167], v[82:83], v[166:167]
	v_mul_f32_e32 v192, 0xbfb8aa3b, v164
	v_mul_f32_e32 v193, 0xbfb8aa3b, v165
	v_exp_f32_e32 v192, v192
	v_exp_f32_e32 v193, v193
	v_pk_fma_f32 v[168:169], v[144:145], v[48:49], v[168:169]
	v_pk_mul_f32 v[170:171], v[46:47], v[170:171]
	v_pk_fma_f32 v[168:169], v[128:129], v[52:53], v[168:169]
	v_pk_add_f32 v[192:193], v[192:193], 1.0 op_sel_hi:[1,0]
	v_pk_add_f32 v[168:169], v[56:57], v[168:169]
	v_rcp_f32_e32 v195, v193
	v_pk_fma_f32 v[170:171], v[146:147], v[50:51], v[170:171]
	v_fma_f32 v202, -v193, v195, 1.0
	v_fmac_f32_e32 v195, v202, v195
	v_div_fixup_f32 v193, v195, v193, 1.0
	v_rcp_f32_e32 v195, v192
	v_pk_fma_f32 v[170:171], v[130:131], v[54:55], v[170:171]
	v_fma_f32 v202, -v192, v195, 1.0
	v_fmac_f32_e32 v195, v202, v195
	v_div_fixup_f32 v192, v195, v192, 1.0
	v_mul_f32_e32 v194, 0xbfb8aa3b, v166
	v_mul_f32_e32 v195, 0xbfb8aa3b, v167
	v_exp_f32_e32 v194, v194
	v_exp_f32_e32 v195, v195
	v_pk_add_f32 v[170:171], v[58:59], v[170:171]
	v_pk_mul_f32 v[192:193], v[164:165], v[192:193]
	v_pk_add_f32 v[194:195], v[194:195], 1.0 op_sel_hi:[1,0]
	s_nop 0
	v_rcp_f32_e32 v203, v195
	v_pk_mul_f32 v[192:193], v[160:161], v[192:193]
	v_fma_f32 v204, -v195, v203, 1.0
	v_fmac_f32_e32 v203, v204, v203
	v_div_fixup_f32 v195, v203, v195, 1.0
	v_rcp_f32_e32 v203, v194
	v_cvt_pk_bf16_f32 v192, v192, v193
	v_fma_f32 v204, -v194, v203, 1.0
	v_fmac_f32_e32 v203, v204, v203
	v_div_fixup_f32 v194, v203, v194, 1.0
	v_mul_f32_e32 v202, 0xbfb8aa3b, v168
	v_mul_f32_e32 v203, 0xbfb8aa3b, v169
	v_exp_f32_e32 v202, v202
	v_exp_f32_e32 v203, v203
	v_pk_mul_f32 v[194:195], v[166:167], v[194:195]
	v_pk_add_f32 v[202:203], v[202:203], 1.0 op_sel_hi:[1,0]
	s_nop 0
	v_rcp_f32_e32 v205, v203
	v_pk_mul_f32 v[194:195], v[162:163], v[194:195]
	v_fma_f32 v206, -v203, v205, 1.0
	v_fmac_f32_e32 v205, v206, v205
	v_div_fixup_f32 v203, v205, v203, 1.0
	v_rcp_f32_e32 v205, v202
	v_cvt_pk_bf16_f32 v193, v194, v195
	v_fma_f32 v206, -v202, v205, 1.0
	v_fmac_f32_e32 v205, v206, v205
	v_div_fixup_f32 v202, v205, v202, 1.0
	v_mul_f32_e32 v204, 0xbfb8aa3b, v170
	v_mul_f32_e32 v205, 0xbfb8aa3b, v171
	v_exp_f32_e32 v204, v204
	v_exp_f32_e32 v205, v205
	v_pk_mul_f32 v[202:203], v[168:169], v[202:203]
	v_pk_add_f32 v[204:205], v[204:205], 1.0 op_sel_hi:[1,0]
	s_nop 0
	v_rcp_f32_e32 v207, v205
	v_pk_mul_f32 v[202:203], v[156:157], v[202:203]
	v_fma_f32 v208, -v205, v207, 1.0
	v_fmac_f32_e32 v207, v208, v207
	v_div_fixup_f32 v205, v207, v205, 1.0
	v_rcp_f32_e32 v207, v204
	v_cvt_pk_bf16_f32 v194, v202, v203
	v_mov_b64_e32 v[202:203], s[0:1]
	v_mad_i64_i32 v[202:203], s[26:27], v201, s21, v[202:203]
	v_fma_f32 v208, -v204, v207, 1.0
	v_fmac_f32_e32 v207, v208, v207
	v_div_fixup_f32 v204, v207, v204, 1.0
	v_pk_mul_f32 v[204:205], v[170:171], v[204:205]
	v_lshl_add_u64 v[202:203], v[182:183], 1, v[202:203]
	v_pk_mul_f32 v[204:205], v[158:159], v[204:205]
	s_nop 0
	v_cvt_pk_bf16_f32 v195, v204, v205
	global_store_dwordx4 v[202:203], v[192:195], off
	s_and_saveexec_b64 s[26:27], s[6:7]
	s_cbranch_execz .LBB0_1005
	s_mul_i32 s28, s19, 0x10800
	s_mul_hi_i32 s21, s19, 0x10800
	s_add_u32 s28, s46, s28
	s_addc_u32 s29, s47, s21
	v_lshl_add_u64 v[192:193], v[182:183], 2, s[28:29]
	global_store_dwordx4 v[192:193], v[164:167], off
	global_store_dwordx4 v[192:193], v[168:171], off offset:16
	s_nop 0
	v_add_co_u32_e32 v164, vcc, 0x5000, v192
	s_nop 1
	v_addc_co_u32_e32 v165, vcc, 0, v193, vcc
	global_store_dwordx4 v[164:165], v[160:163], off offset:2048
	global_store_dwordx4 v[164:165], v[156:159], off offset:2064
	s_nop 1
	v_add_co_u32_e32 v156, vcc, 0xb000, v192
	s_nop 1
	v_addc_co_u32_e32 v157, vcc, 0, v193, vcc
	global_store_dwordx4 v[156:157], v[152:155], off
	global_store_dwordx4 v[156:157], v[144:147], off offset:16

.LBB0_1180:
	s_add_u32 s16, s14, 0x100
	s_addc_u32 s17, s15, 0
	s_add_i32 s45, 0, 0x10000
	v_add_u32_e32 v144, s45, v200
	ds_read_b128 v[132:135], v144
	ds_read_b128 v[136:139], v144 offset:1024
	ds_read_b128 v[140:143], v144 offset:2048
	ds_read_b128 v[144:147], v144 offset:3072
	s_cmpk_eq_i32 s44, 0x54
	s_cselect_b32 s21, s1, s17
	s_cselect_b32 s20, s0, s16
	s_cselect_b32 s19, s7, s43
	s_cselect_b32 s18, s6, s42
	s_add_i32 m0, s28, 0xc000
	ds_read_b128 v[148:151], v202
	ds_read_b128 v[152:155], v202 offset:1024
	ds_read_b128 v[156:159], v202 offset:2048
	ds_read_b128 v[160:163], v202 offset:3072
	ds_read_b128 v[164:167], v202 offset:4096
	ds_read_b128 v[168:171], v202 offset:5120
	ds_read_b128 v[172:175], v202 offset:6144
	ds_read_b128 v[186:189], v202 offset:7168
	global_load_lds_dwordx4 v182, s[14:15]
	s_add_i32 m0, s28, 0xe000
	s_nop 0
	global_load_lds_dwordx4 v184, s[14:15]
	s_waitcnt lgkmcnt(8)
	s_barrier
	s_waitcnt lgkmcnt(0)
	s_setprio 1
	v_mfma_f32_16x16x32_bf16 v[128:131], v[132:135], v[148:151], v[128:131]
	v_mfma_f32_16x16x32_bf16 v[128:131], v[136:139], v[152:155], v[128:131]
	v_mfma_f32_16x16x32_bf16 v[112:115], v[136:139], v[160:163], v[112:115]
	v_mfma_f32_16x16x32_bf16 v[112:115], v[132:135], v[156:159], v[112:115]
	v_mfma_f32_16x16x32_bf16 v[96:99], v[132:135], v[164:167], v[96:99]
	v_mfma_f32_16x16x32_bf16 v[96:99], v[136:139], v[168:171], v[96:99]
	v_mfma_f32_16x16x32_bf16 v[80:83], v[136:139], v[186:189], v[80:83]
	v_mfma_f32_16x16x32_bf16 v[80:83], v[132:135], v[172:175], v[80:83]
	v_mfma_f32_16x16x32_bf16 v[76:79], v[140:143], v[172:175], v[76:79]
	v_mfma_f32_16x16x32_bf16 v[76:79], v[144:147], v[186:189], v[76:79]
	v_mfma_f32_16x16x32_bf16 v[92:95], v[144:147], v[168:171], v[92:95]
	v_mfma_f32_16x16x32_bf16 v[92:95], v[140:143], v[164:167], v[92:95]
	v_mfma_f32_16x16x32_bf16 v[108:111], v[140:143], v[156:159], v[108:111]
	v_mfma_f32_16x16x32_bf16 v[108:111], v[144:147], v[160:163], v[108:111]
	v_mfma_f32_16x16x32_bf16 v[124:127], v[144:147], v[152:155], v[124:127]
	s_barrier
	v_mfma_f32_16x16x32_bf16 v[124:127], v[140:143], v[148:151], v[124:127]
	s_setprio 0
	s_add_i32 s46, 0, 0x14000
	s_add_i32 s14, s45, s27
	v_add_u32_e32 v203, s46, v200
	v_lshl_add_u64 v[212:213], s[18:19], 0, v[2:3]
	s_mov_b32 m0, s14
	ds_read_b128 v[190:193], v203
	ds_read_b128 v[194:197], v203 offset:1024
	ds_read_b128 v[204:207], v203 offset:2048
	ds_read_b128 v[208:211], v203 offset:3072
	global_load_lds_dwordx4 v[212:213], off
	v_lshl_add_u64 v[214:215], s[18:19], 0, v[176:177]
	s_add_i32 m0, s14, 0x2000
	s_nop 0
	global_load_lds_dwordx4 v[214:215], off
	s_barrier
	s_waitcnt lgkmcnt(0)
	s_setprio 1
	v_mfma_f32_16x16x32_bf16 v[120:123], v[190:193], v[148:151], v[120:123]
	v_mfma_f32_16x16x32_bf16 v[120:123], v[194:197], v[152:155], v[120:123]
	v_mfma_f32_16x16x32_bf16 v[104:107], v[194:197], v[160:163], v[104:107]
	v_mfma_f32_16x16x32_bf16 v[104:107], v[190:193], v[156:159], v[104:107]
	v_mfma_f32_16x16x32_bf16 v[88:91], v[190:193], v[164:167], v[88:91]
	v_mfma_f32_16x16x32_bf16 v[88:91], v[194:197], v[168:171], v[88:91]
	v_mfma_f32_16x16x32_bf16 v[72:75], v[194:197], v[186:189], v[72:75]
	v_mfma_f32_16x16x32_bf16 v[72:75], v[190:193], v[172:175], v[72:75]
	v_mfma_f32_16x16x32_bf16 v[68:71], v[204:207], v[172:175], v[68:71]
	v_mfma_f32_16x16x32_bf16 v[68:71], v[208:211], v[186:189], v[68:71]
	v_mfma_f32_16x16x32_bf16 v[84:87], v[208:211], v[168:171], v[84:87]
	v_mfma_f32_16x16x32_bf16 v[84:87], v[204:207], v[164:167], v[84:87]
	v_mfma_f32_16x16x32_bf16 v[100:103], v[204:207], v[156:159], v[100:103]
	v_mfma_f32_16x16x32_bf16 v[100:103], v[208:211], v[160:163], v[100:103]
	v_mfma_f32_16x16x32_bf16 v[116:119], v[208:211], v[152:155], v[116:119]
	s_barrier
	v_mfma_f32_16x16x32_bf16 v[116:119], v[204:207], v[148:151], v[116:119]
	s_setprio 0
	s_mov_b32 m0, s28
	v_lshl_add_u64 v[216:217], s[20:21], 0, v[180:181]
	ds_read_b128 v[148:151], v202 offset:16384
	ds_read_b128 v[152:155], v202 offset:17408
	ds_read_b128 v[156:159], v202 offset:18432
	ds_read_b128 v[160:163], v202 offset:19456
	ds_read_b128 v[164:167], v202 offset:20480
	ds_read_b128 v[168:171], v202 offset:21504
	ds_read_b128 v[172:175], v202 offset:22528
	ds_read_b128 v[186:189], v202 offset:23552
	global_load_lds_dwordx4 v[216:217], off
	v_lshl_add_u64 v[218:219], s[20:21], 0, v[178:179]
	s_mov_b32 m0, s29
	s_nop 0
	global_load_lds_dwordx4 v[218:219], off
	s_waitcnt vmcnt(10)
	s_barrier
	s_waitcnt lgkmcnt(0)
	s_setprio 1
	v_mfma_f32_16x16x32_bf16 v[64:67], v[132:135], v[148:151], v[64:67]
	v_mfma_f32_16x16x32_bf16 v[64:67], v[136:139], v[152:155], v[64:67]
	v_mfma_f32_16x16x32_bf16 v[48:51], v[136:139], v[160:163], v[48:51]
	v_mfma_f32_16x16x32_bf16 v[48:51], v[132:135], v[156:159], v[48:51]
	v_mfma_f32_16x16x32_bf16 v[32:35], v[132:135], v[164:167], v[32:35]
	v_mfma_f32_16x16x32_bf16 v[32:35], v[136:139], v[168:171], v[32:35]
	v_mfma_f32_16x16x32_bf16 v[16:19], v[136:139], v[186:189], v[16:19]
	v_mfma_f32_16x16x32_bf16 v[16:19], v[132:135], v[172:175], v[16:19]
	v_mfma_f32_16x16x32_bf16 v[12:15], v[140:143], v[172:175], v[12:15]
	v_mfma_f32_16x16x32_bf16 v[12:15], v[144:147], v[186:189], v[12:15]
	v_mfma_f32_16x16x32_bf16 v[28:31], v[144:147], v[168:171], v[28:31]
	v_mfma_f32_16x16x32_bf16 v[28:31], v[140:143], v[164:167], v[28:31]
	v_mfma_f32_16x16x32_bf16 v[44:47], v[140:143], v[156:159], v[44:47]
	v_mfma_f32_16x16x32_bf16 v[44:47], v[144:147], v[160:163], v[44:47]
	v_mfma_f32_16x16x32_bf16 v[60:63], v[144:147], v[152:155], v[60:63]
	s_barrier
	v_mfma_f32_16x16x32_bf16 v[60:63], v[140:143], v[148:151], v[60:63]
	s_setprio 0
	s_add_u32 s14, s18, 0x160000
	s_addc_u32 s15, s19, 0
	s_add_i32 s45, s46, s27
	v_lshl_add_u64 v[132:133], s[14:15], 0, v[2:3]
	s_mov_b32 m0, s45
	s_nop 0
	global_load_lds_dwordx4 v[132:133], off
	v_lshl_add_u64 v[132:133], s[14:15], 0, v[176:177]
	s_add_i32 m0, s45, 0x2000
	s_nop 0
	global_load_lds_dwordx4 v[132:133], off
	s_add_i32 s45, 0, 0x18000
	v_add_u32_e32 v144, s45, v200
	ds_read_b128 v[132:135], v144
	ds_read_b128 v[136:139], v144 offset:1024
	ds_read_b128 v[140:143], v144 offset:2048
	ds_read_b128 v[144:147], v144 offset:3072
	s_waitcnt vmcnt(6)
	s_barrier
	s_setprio 1
	v_mfma_f32_16x16x32_bf16 v[56:59], v[190:193], v[148:151], v[56:59]
	v_mfma_f32_16x16x32_bf16 v[56:59], v[194:197], v[152:155], v[56:59]
	v_mfma_f32_16x16x32_bf16 v[40:43], v[194:197], v[160:163], v[40:43]
	v_mfma_f32_16x16x32_bf16 v[40:43], v[190:193], v[156:159], v[40:43]
	v_mfma_f32_16x16x32_bf16 v[24:27], v[190:193], v[164:167], v[24:27]
	v_mfma_f32_16x16x32_bf16 v[24:27], v[194:197], v[168:171], v[24:27]
	v_mfma_f32_16x16x32_bf16 v[8:11], v[194:197], v[186:189], v[8:11]
	v_mfma_f32_16x16x32_bf16 v[8:11], v[190:193], v[172:175], v[8:11]
	v_mfma_f32_16x16x32_bf16 v[4:7], v[204:207], v[172:175], v[4:7]
	v_mfma_f32_16x16x32_bf16 v[4:7], v[208:211], v[186:189], v[4:7]
	v_mfma_f32_16x16x32_bf16 v[20:23], v[208:211], v[168:171], v[20:23]
	v_mfma_f32_16x16x32_bf16 v[20:23], v[204:207], v[164:167], v[20:23]
	v_mfma_f32_16x16x32_bf16 v[36:39], v[204:207], v[156:159], v[36:39]
	v_mfma_f32_16x16x32_bf16 v[36:39], v[208:211], v[160:163], v[36:39]
	v_mfma_f32_16x16x32_bf16 v[52:55], v[208:211], v[152:155], v[52:55]
	s_barrier
	v_mfma_f32_16x16x32_bf16 v[52:55], v[204:207], v[148:151], v[52:55]
	s_setprio 0
	s_add_u32 s14, s20, 0x160000
	s_addc_u32 s15, s21, 0
	s_mov_b32 m0, s30
	ds_read_b128 v[148:151], v202 offset:32768
	ds_read_b128 v[152:155], v202 offset:33792
	ds_read_b128 v[156:159], v202 offset:34816
	ds_read_b128 v[160:163], v202 offset:35840
	ds_read_b128 v[164:167], v202 offset:36864
	ds_read_b128 v[168:171], v202 offset:37888
	ds_read_b128 v[172:175], v202 offset:38912
	ds_read_b128 v[186:189], v202 offset:39936
	global_load_lds_dwordx4 v180, s[14:15]
	s_mov_b32 m0, s31
	s_nop 0
	global_load_lds_dwordx4 v178, s[14:15]
	s_waitcnt lgkmcnt(8)
	s_barrier
	s_waitcnt lgkmcnt(0)
	s_setprio 1
	v_mfma_f32_16x16x32_bf16 v[128:131], v[132:135], v[148:151], v[128:131]
	v_mfma_f32_16x16x32_bf16 v[128:131], v[136:139], v[152:155], v[128:131]
	v_mfma_f32_16x16x32_bf16 v[112:115], v[136:139], v[160:163], v[112:115]
	v_mfma_f32_16x16x32_bf16 v[112:115], v[132:135], v[156:159], v[112:115]
	v_mfma_f32_16x16x32_bf16 v[96:99], v[132:135], v[164:167], v[96:99]
	v_mfma_f32_16x16x32_bf16 v[96:99], v[136:139], v[168:171], v[96:99]
	v_mfma_f32_16x16x32_bf16 v[80:83], v[136:139], v[186:189], v[80:83]
	v_mfma_f32_16x16x32_bf16 v[80:83], v[132:135], v[172:175], v[80:83]
	v_mfma_f32_16x16x32_bf16 v[76:79], v[140:143], v[172:175], v[76:79]
	v_mfma_f32_16x16x32_bf16 v[76:79], v[144:147], v[186:189], v[76:79]
	v_mfma_f32_16x16x32_bf16 v[92:95], v[144:147], v[168:171], v[92:95]
	v_mfma_f32_16x16x32_bf16 v[92:95], v[140:143], v[164:167], v[92:95]
	v_mfma_f32_16x16x32_bf16 v[108:111], v[140:143], v[156:159], v[108:111]
	v_mfma_f32_16x16x32_bf16 v[108:111], v[144:147], v[160:163], v[108:111]
	v_mfma_f32_16x16x32_bf16 v[124:127], v[144:147], v[152:155], v[124:127]
	s_barrier
	v_mfma_f32_16x16x32_bf16 v[124:127], v[140:143], v[148:151], v[124:127]
	s_setprio 0
	s_add_i32 s20, 0, 0x1c000
	s_add_i32 s14, s45, s27
	v_add_u32_e32 v203, s20, v200
	v_lshl_add_u64 v[212:213], v[212:213], 0, s[2:3]
	s_mov_b32 m0, s14
	ds_read_b128 v[190:193], v203
	ds_read_b128 v[194:197], v203 offset:1024
	ds_read_b128 v[204:207], v203 offset:2048
	ds_read_b128 v[208:211], v203 offset:3072
	global_load_lds_dwordx4 v[212:213], off
	v_lshl_add_u64 v[212:213], v[214:215], 0, s[2:3]
	s_add_i32 m0, s14, 0x2000
	s_nop 0
	global_load_lds_dwordx4 v[212:213], off
	s_barrier
	s_waitcnt lgkmcnt(0)
	s_setprio 1
	v_mfma_f32_16x16x32_bf16 v[120:123], v[190:193], v[148:151], v[120:123]
	v_mfma_f32_16x16x32_bf16 v[120:123], v[194:197], v[152:155], v[120:123]
	v_mfma_f32_16x16x32_bf16 v[104:107], v[194:197], v[160:163], v[104:107]
	v_mfma_f32_16x16x32_bf16 v[104:107], v[190:193], v[156:159], v[104:107]
	v_mfma_f32_16x16x32_bf16 v[88:91], v[190:193], v[164:167], v[88:91]
	v_mfma_f32_16x16x32_bf16 v[88:91], v[194:197], v[168:171], v[88:91]
	v_mfma_f32_16x16x32_bf16 v[72:75], v[194:197], v[186:189], v[72:75]
	v_mfma_f32_16x16x32_bf16 v[72:75], v[190:193], v[172:175], v[72:75]
	v_mfma_f32_16x16x32_bf16 v[68:71], v[204:207], v[172:175], v[68:71]
	v_mfma_f32_16x16x32_bf16 v[68:71], v[208:211], v[186:189], v[68:71]
	v_mfma_f32_16x16x32_bf16 v[84:87], v[208:211], v[168:171], v[84:87]
	v_mfma_f32_16x16x32_bf16 v[84:87], v[204:207], v[164:167], v[84:87]
	v_mfma_f32_16x16x32_bf16 v[100:103], v[204:207], v[156:159], v[100:103]
	v_mfma_f32_16x16x32_bf16 v[100:103], v[208:211], v[160:163], v[100:103]
	v_mfma_f32_16x16x32_bf16 v[116:119], v[208:211], v[152:155], v[116:119]
	s_barrier
	v_mfma_f32_16x16x32_bf16 v[116:119], v[204:207], v[148:151], v[116:119]
	s_setprio 0
	s_mov_b32 m0, s36
	v_lshl_add_u64 v[212:213], v[216:217], 0, s[2:3]
	ds_read_b128 v[148:151], v202 offset:49152
	ds_read_b128 v[152:155], v202 offset:50176
	ds_read_b128 v[156:159], v202 offset:51200
	ds_read_b128 v[160:163], v202 offset:52224
	ds_read_b128 v[164:167], v202 offset:53248
	ds_read_b128 v[168:171], v202 offset:54272
	ds_read_b128 v[172:175], v202 offset:55296
	ds_read_b128 v[186:189], v202 offset:56320
	global_load_lds_dwordx4 v[212:213], off
	v_lshl_add_u64 v[212:213], v[218:219], 0, s[2:3]
	s_mov_b32 m0, s37
	s_nop 0
	global_load_lds_dwordx4 v[212:213], off
	s_barrier
	s_waitcnt lgkmcnt(0)
	s_setprio 1
	v_mfma_f32_16x16x32_bf16 v[64:67], v[132:135], v[148:151], v[64:67]
	v_mfma_f32_16x16x32_bf16 v[64:67], v[136:139], v[152:155], v[64:67]
	v_mfma_f32_16x16x32_bf16 v[48:51], v[136:139], v[160:163], v[48:51]
	v_mfma_f32_16x16x32_bf16 v[48:51], v[132:135], v[156:159], v[48:51]
	v_mfma_f32_16x16x32_bf16 v[32:35], v[132:135], v[164:167], v[32:35]
	v_mfma_f32_16x16x32_bf16 v[32:35], v[136:139], v[168:171], v[32:35]
	v_mfma_f32_16x16x32_bf16 v[16:19], v[136:139], v[186:189], v[16:19]
	v_mfma_f32_16x16x32_bf16 v[16:19], v[132:135], v[172:175], v[16:19]
	v_mfma_f32_16x16x32_bf16 v[12:15], v[140:143], v[172:175], v[12:15]
	v_mfma_f32_16x16x32_bf16 v[12:15], v[144:147], v[186:189], v[12:15]
	v_mfma_f32_16x16x32_bf16 v[28:31], v[144:147], v[168:171], v[28:31]
	v_mfma_f32_16x16x32_bf16 v[28:31], v[140:143], v[164:167], v[28:31]
	v_mfma_f32_16x16x32_bf16 v[44:47], v[140:143], v[156:159], v[44:47]
	v_mfma_f32_16x16x32_bf16 v[44:47], v[144:147], v[160:163], v[44:47]
	v_mfma_f32_16x16x32_bf16 v[60:63], v[144:147], v[152:155], v[60:63]
	s_barrier
	v_mfma_f32_16x16x32_bf16 v[60:63], v[140:143], v[148:151], v[60:63]
	s_setprio 0
	s_add_u32 s14, s18, 0x160080
	s_addc_u32 s15, s19, 0
	s_add_i32 s18, s20, s27
	v_lshl_add_u64 v[132:133], s[14:15], 0, v[2:3]
	s_mov_b32 m0, s18
	s_nop 0
	global_load_lds_dwordx4 v[132:133], off
	v_lshl_add_u64 v[132:133], s[14:15], 0, v[176:177]
	s_add_i32 m0, s18, 0x2000
	s_nop 0
	global_load_lds_dwordx4 v[132:133], off
	s_waitcnt vmcnt(6)
	s_barrier
	s_setprio 1
	v_mfma_f32_16x16x32_bf16 v[56:59], v[190:193], v[148:151], v[56:59]
	v_mfma_f32_16x16x32_bf16 v[56:59], v[194:197], v[152:155], v[56:59]
	v_mfma_f32_16x16x32_bf16 v[40:43], v[194:197], v[160:163], v[40:43]
	v_mfma_f32_16x16x32_bf16 v[40:43], v[190:193], v[156:159], v[40:43]
	v_mfma_f32_16x16x32_bf16 v[24:27], v[190:193], v[164:167], v[24:27]
	v_mfma_f32_16x16x32_bf16 v[24:27], v[194:197], v[168:171], v[24:27]
	v_mfma_f32_16x16x32_bf16 v[8:11], v[194:197], v[186:189], v[8:11]
	v_mfma_f32_16x16x32_bf16 v[8:11], v[190:193], v[172:175], v[8:11]
	v_mfma_f32_16x16x32_bf16 v[4:7], v[204:207], v[172:175], v[4:7]
	v_mfma_f32_16x16x32_bf16 v[4:7], v[208:211], v[186:189], v[4:7]
	v_mfma_f32_16x16x32_bf16 v[20:23], v[208:211], v[168:171], v[20:23]
	v_mfma_f32_16x16x32_bf16 v[20:23], v[204:207], v[164:167], v[20:23]
	v_mfma_f32_16x16x32_bf16 v[36:39], v[204:207], v[156:159], v[36:39]
	v_mfma_f32_16x16x32_bf16 v[36:39], v[208:211], v[160:163], v[36:39]
	v_mfma_f32_16x16x32_bf16 v[52:55], v[208:211], v[152:155], v[52:55]
	s_barrier
	v_mfma_f32_16x16x32_bf16 v[52:55], v[204:207], v[148:151], v[52:55]
	s_setprio 0
	s_add_i32 s44, s44, 2
	s_add_u32 s42, s42, 0x100
	s_addc_u32 s43, s43, 0
	s_cmpk_gt_u32 s44, 0x55
	s_mov_b64 s[14:15], s[16:17]
	s_cbranch_scc0 .LBB0_1180
	s_cmp_lt_i32 s41, 32
	s_mov_b64 s[14:15], 0
	s_cbranch_scc1 .LBB0_1183
	s_sub_i32 s14, s41, 32
	s_lshr_b32 s14, s14, 4
	s_add_i32 s14, s14, 1
	s_mul_hi_u32 s15, s14, 0x3000
	s_mulk_i32 s14, 0x3000
